# adds: K-loop prologue issues all 7 half-tile DMA groups before its first wait; relaxed first-iteration waits after unit epilogues (G1,G4); residual loads of the fused-norm epilogues hoisted above the
# speedup vs baseline: 1.0012x; 1.0012x over previous
; __device__ __forceinline__ float bf_lo(unsigned w) { return __uint_as_float(w << 16); }
; #define PG8_BAR __builtin_amdgcn_s_barrier()
;     __device__ __forceinline__ void fused(f32x4 (&acc)[2][2][4][2], const Unit& u, int wr, int wc, int fr, int fq, PG8_LAS unsigned char* lds, int wid, int lane) const {
;     ...
;         for (int ai = 0; ai < 2; ++ai) {
;             h16x8 hraw[4][2]; u32x4 eraw[4][2];
; #pragma unroll
;             for (int m = 0; m < 4; ++m) { const size_t off = (size_t)(u.pm * BM + ai * HALF + wr * 64 + m * 16 + fr) * ld + col0;
; #pragma unroll
;                 for (int bj = 0; bj < 2; ++bj) { hraw[m][bj] = *(const h16x8*)(H + off + bj * HALF); if (MODE != 0) eraw[m][bj] = *(const u32x4*)(E + off + bj * HALF); } }
; #pragma unroll
;             for (int m = 0; m < 4; ++m) { const size_t off = (size_t)(u.pm * BM + ai * HALF + wr * 64 + m * 16 + fr) * ld + col0;
; #pragma unroll
;                 for (int bj = 0; bj < 2; ++bj) { const f32x8 hv = __builtin_convertvector(hraw[m][bj], f32x8); f32x8 r8;
; #pragma unroll
;                     for (int n = 0; n < 2; ++n) { f32x4 r; const f32x4 a = acc[ai][bj][m][n];
;                         if (MODE == 0) { r[0] = hv[4 * n] + a[0]; r[1] = hv[4 * n + 1] + a[1]; r[2] = hv[4 * n + 2] + a[2]; r[3] = hv[4 * n + 3] + a[3]; }
;                         else { const unsigned e0 = n ? eraw[m][bj].z : eraw[m][bj].x, e1 = n ? eraw[m][bj].w : eraw[m][bj].y;
;                             r[0] = hv[4 * n] + sigmoidf_fast(a[0]) * bf_lo(e0); r[1] = hv[4 * n + 1] + sigmoidf_fast(a[1]) * bf_hi(e0); r[2] = hv[4 * n + 2] + sigmoidf_fast(a[2]) * bf_lo(e1); r[3] = hv[4 * n + 3] + sigmoidf_fast(a[3]) * bf_hi(e1); }
;                         acc[ai][bj][m][n] = r; r8[4 * n] = r[0]; r8[4 * n + 1] = r[1]; r8[4 * n + 2] = r[2]; r8[4 * n + 3] = r[3]; }
;                     *(h16x8*)(H + off + bj * HALF) = __builtin_convertvector(r8, h16x8); }
;                 asm volatile("" : "+v"(acc[ai][0][m][0]), "+v"(acc[ai][0][m][1]), "+v"(acc[ai][1][m][0]), "+v"(acc[ai][1][m][1])); }
; template <class Epi, class Sched, bool ALIGN_EPI = false, bool SP2 = false, bool KHOOK = false>
; __device__ __forceinline__ void gemm_phase(PG8_LAS unsigned char* lds, const Gemm g, const Sched& S, const Epi& E, const int tid_in) {
;     ...
;     PG8_WAIT_V(0);
;     if constexpr (!ALIGN_EPI) { if (wr == 0) PG8_BAR; }
;     PG8_BAR;
.LBB0_953:
	s_lshl_b32 s4, s36, 5
	s_lshl_b32 s5, s0, 8
	v_lshrrev_b32_e32 v122, 1, v173
	s_or_b32 s4, s5, s4
	s_lshl_b32 s18, s33, 8
	v_and_or_b32 v160, v122, 24, s4
	s_add_i32 s4, s18, s45
	v_or_b32_e32 v162, s4, v174
	v_ashrrev_i32_e32 v161, 31, v160
	v_readlane_b32 s4, v252, 57
	v_lshlrev_b64 v[158:159], 1, v[160:161]
	v_readlane_b32 s5, v252, 58
	v_ashrrev_i32_e32 v163, 31, v162
	v_lshlrev_b64 v[180:181], 12, v[162:163]
	v_lshl_add_u64 v[164:165], s[4:5], 0, v[158:159]
	v_lshl_add_u64 v[126:127], v[164:165], 0, v[180:181]
	global_load_dwordx4 v[122:125], v[126:127], off
	s_nop 0
	global_load_dwordx4 v[126:129], v[126:127], off offset:256
	v_or_b32_e32 v138, 16, v162
	v_ashrrev_i32_e32 v139, 31, v138
	v_lshlrev_b64 v[170:171], 12, v[138:139]
	v_lshl_add_u64 v[138:139], v[164:165], 0, v[170:171]
	global_load_dwordx4 v[176:179], v[138:139], off
	global_load_dwordx4 v[154:157], v[138:139], off offset:256
	v_or_b32_e32 v138, 32, v162
	v_ashrrev_i32_e32 v139, 31, v138
	v_lshlrev_b64 v[168:169], 12, v[138:139]
	v_lshl_add_u64 v[138:139], v[164:165], 0, v[168:169]
	global_load_dwordx4 v[150:153], v[138:139], off
	global_load_dwordx4 v[146:149], v[138:139], off offset:256
	v_or_b32_e32 v138, 48, v162
	v_ashrrev_i32_e32 v139, 31, v138
	v_lshlrev_b64 v[166:167], 12, v[138:139]
	v_lshl_add_u64 v[138:139], v[164:165], 0, v[166:167]
	global_load_dwordx4 v[142:145], v[138:139], off
	s_nop 0
	global_load_dwordx4 v[138:141], v[138:139], off offset:256
	s_waitcnt vmcnt(0)
	s_cmpk_gt_u32 s2, 0xff
	s_cbranch_scc1 .LBB0_955
	s_barrier
.LBB0_955:
	s_barrier
	v_lshl_add_u64 v[180:181], s[4:5], 0, v[180:181]
	v_lshl_add_u64 v[180:181], v[180:181], 0, v[158:159]
	v_and_b32_e32 v32, 63, v173
	s_waitcnt vmcnt(0)
	v_cvt_f32_f16_e32 v182, v125
	v_cvt_f32_f16_sdwa v183, v125 dst_sel:DWORD dst_unused:UNUSED_PAD src0_sel:WORD_1
	v_cvt_f32_f16_e32 v184, v124
	v_cvt_f32_f16_sdwa v185, v124 dst_sel:DWORD dst_unused:UNUSED_PAD src0_sel:WORD_1
	v_cvt_f32_f16_e32 v124, v123
	v_cvt_f32_f16_sdwa v125, v123 dst_sel:DWORD dst_unused:UNUSED_PAD src0_sel:WORD_1
	v_cvt_f32_f16_e32 v186, v122
	v_cvt_f32_f16_sdwa v187, v122 dst_sel:DWORD dst_unused:UNUSED_PAD src0_sel:WORD_1
	v_pk_add_f32 v[114:115], v[114:115], v[184:185]
	v_pk_add_f32 v[120:121], v[120:121], v[124:125]
	v_pk_add_f32 v[116:117], v[116:117], v[182:183]
	v_pk_add_f32 v[118:119], v[118:119], v[186:187]
	v_cvt_pk_f16_f32 v125, v116, v117
	v_cvt_pk_f16_f32 v124, v114, v115
	v_cvt_pk_f16_f32 v123, v120, v121
	v_cvt_pk_f16_f32 v122, v118, v119
	global_store_dwordx4 v[180:181], v[122:125], off
	v_cvt_f32_f16_e32 v182, v126
	v_cvt_f32_f16_sdwa v183, v126 dst_sel:DWORD dst_unused:UNUSED_PAD src0_sel:WORD_1
	v_cvt_f32_f16_e32 v124, v129
	v_cvt_f32_f16_sdwa v125, v129 dst_sel:DWORD dst_unused:UNUSED_PAD src0_sel:WORD_1
	v_cvt_f32_f16_e32 v122, v128
	v_cvt_f32_f16_sdwa v123, v128 dst_sel:DWORD dst_unused:UNUSED_PAD src0_sel:WORD_1
	v_cvt_f32_f16_e32 v128, v127
	v_cvt_f32_f16_sdwa v129, v127 dst_sel:DWORD dst_unused:UNUSED_PAD src0_sel:WORD_1
	v_pk_add_f32 v[126:127], v[106:107], v[182:183]
	v_pk_add_f32 v[122:123], v[102:103], v[122:123]
	v_pk_add_f32 v[124:125], v[104:105], v[124:125]
	v_pk_add_f32 v[128:129], v[108:109], v[128:129]
	v_cvt_pk_f16_f32 v105, v124, v125
	v_cvt_pk_f16_f32 v104, v122, v123
	v_cvt_pk_f16_f32 v103, v128, v129
	v_cvt_pk_f16_f32 v102, v126, v127
	global_store_dwordx4 v[180:181], v[102:105], off offset:256
	v_cvt_f32_f16_e32 v108, v177
	v_cvt_f32_f16_sdwa v109, v177 dst_sel:DWORD dst_unused:UNUSED_PAD src0_sel:WORD_1
	v_cvt_f32_f16_e32 v104, v179
	v_cvt_f32_f16_sdwa v105, v179 dst_sel:DWORD dst_unused:UNUSED_PAD src0_sel:WORD_1
	v_cvt_f32_f16_e32 v102, v178
	v_cvt_f32_f16_sdwa v103, v178 dst_sel:DWORD dst_unused:UNUSED_PAD src0_sel:WORD_1
	v_cvt_f32_f16_e32 v106, v176
	v_cvt_f32_f16_sdwa v107, v176 dst_sel:DWORD dst_unused:UNUSED_PAD src0_sel:WORD_1
	v_pk_add_f32 v[108:109], v[136:137], v[108:109]
	v_pk_add_f32 v[102:103], v[130:131], v[102:103]
	v_pk_add_f32 v[104:105], v[132:133], v[104:105]
	v_pk_add_f32 v[106:107], v[134:135], v[106:107]
	v_lshl_add_u64 v[130:131], s[4:5], 0, v[170:171]
	v_cvt_pk_f16_f32 v135, v104, v105
	v_cvt_pk_f16_f32 v134, v102, v103
	v_cvt_pk_f16_f32 v133, v108, v109
	v_cvt_pk_f16_f32 v132, v106, v107
	v_lshl_add_u64 v[130:131], v[130:131], 0, v[158:159]
	global_store_dwordx4 v[130:131], v[132:135], off
	v_cvt_f32_f16_e32 v136, v155
	v_cvt_f32_f16_sdwa v137, v155 dst_sel:DWORD dst_unused:UNUSED_PAD src0_sel:WORD_1
	v_cvt_f32_f16_e32 v132, v157
	v_cvt_f32_f16_sdwa v133, v157 dst_sel:DWORD dst_unused:UNUSED_PAD src0_sel:WORD_1
	v_cvt_f32_f16_e32 v134, v156
	v_cvt_f32_f16_sdwa v135, v156 dst_sel:DWORD dst_unused:UNUSED_PAD src0_sel:WORD_1
	v_cvt_f32_f16_e32 v156, v154
	v_cvt_f32_f16_sdwa v157, v154 dst_sel:DWORD dst_unused:UNUSED_PAD src0_sel:WORD_1
	v_pk_add_f32 v[112:113], v[112:113], v[136:137]
	v_pk_add_f32 v[98:99], v[98:99], v[134:135]
	v_pk_add_f32 v[100:101], v[100:101], v[132:133]
	v_pk_add_f32 v[110:111], v[110:111], v[156:157]
	v_cvt_pk_f16_f32 v135, v100, v101
	v_cvt_pk_f16_f32 v134, v98, v99
	v_cvt_pk_f16_f32 v133, v112, v113
	v_cvt_pk_f16_f32 v132, v110, v111
	global_store_dwordx4 v[130:131], v[132:135], off offset:256
	v_cvt_f32_f16_e32 v130, v153
	v_cvt_f32_f16_sdwa v131, v153 dst_sel:DWORD dst_unused:UNUSED_PAD src0_sel:WORD_1
	v_cvt_f32_f16_e32 v132, v152
	v_cvt_f32_f16_sdwa v133, v152 dst_sel:DWORD dst_unused:UNUSED_PAD src0_sel:WORD_1
	v_cvt_f32_f16_e32 v134, v151
	v_cvt_f32_f16_sdwa v135, v151 dst_sel:DWORD dst_unused:UNUSED_PAD src0_sel:WORD_1
	v_cvt_f32_f16_e32 v136, v150
	v_cvt_f32_f16_sdwa v137, v150 dst_sel:DWORD dst_unused:UNUSED_PAD src0_sel:WORD_1
; __device__ __forceinline__ float bf_lo(unsigned w) { return __uint_as_float(w << 16); }
; __device__ __forceinline__ float bf_hi(unsigned w) { return __uint_as_float(w & 0xffff0000u); }
; __device__ __forceinline__ float sigmoidf_fast(float x) { return __builtin_amdgcn_rcpf(1.0f + __expf(-x)); }
;     __device__ __forceinline__ void fused(f32x4 (&acc)[2][2][4][2], const Unit& u, int wr, int wc, int fr, int fq, PG8_LAS unsigned char* lds, int wid, int lane) const {
;     ...
;             for (int m = 0; m < 4; ++m) { const size_t off = (size_t)(u.pm * BM + ai * HALF + wr * 64 + m * 16 + fr) * ld + col0;
; #pragma unroll
;                 for (int bj = 0; bj < 2; ++bj) { hraw[m][bj] = *(const h16x8*)(H + off + bj * HALF); if (MODE != 0) eraw[m][bj] = *(const u32x4*)(E + off + bj * HALF); } }
; #pragma unroll
;             for (int m = 0; m < 4; ++m) { const size_t off = (size_t)(u.pm * BM + ai * HALF + wr * 64 + m * 16 + fr) * ld + col0;
; #pragma unroll
;                 for (int bj = 0; bj < 2; ++bj) { const f32x8 hv = __builtin_convertvector(hraw[m][bj], f32x8); f32x8 r8;
; #pragma unroll
;                     for (int n = 0; n < 2; ++n) { f32x4 r; const f32x4 a = acc[ai][bj][m][n];
;                         if (MODE == 0) { r[0] = hv[4 * n] + a[0]; r[1] = hv[4 * n + 1] + a[1]; r[2] = hv[4 * n + 2] + a[2]; r[3] = hv[4 * n + 3] + a[3]; }
;                         else { const unsigned e0 = n ? eraw[m][bj].z : eraw[m][bj].x, e1 = n ? eraw[m][bj].w : eraw[m][bj].y;
;                             r[0] = hv[4 * n] + sigmoidf_fast(a[0]) * bf_lo(e0); r[1] = hv[4 * n + 1] + sigmoidf_fast(a[1]) * bf_hi(e0); r[2] = hv[4 * n + 2] + sigmoidf_fast(a[2]) * bf_lo(e1); r[3] = hv[4 * n + 3] + sigmoidf_fast(a[3]) * bf_hi(e1); }
;                         acc[ai][bj][m][n] = r; r8[4 * n] = r[0]; r8[4 * n + 1] = r[1]; r8[4 * n + 2] = r[2]; r8[4 * n + 3] = r[3]; }
;                     *(h16x8*)(H + off + bj * HALF) = __builtin_convertvector(r8, h16x8); }
;                 asm volatile("" : "+v"(acc[ai][0][m][0]), "+v"(acc[ai][0][m][1]), "+v"(acc[ai][1][m][0]), "+v"(acc[ai][1][m][1])); }
	v_pk_add_f32 v[90:91], v[90:91], v[132:133]
	v_pk_add_f32 v[96:97], v[96:97], v[134:135]
	v_pk_add_f32 v[92:93], v[92:93], v[130:131]
	v_pk_add_f32 v[94:95], v[94:95], v[136:137]
	v_lshl_add_u64 v[134:135], s[4:5], 0, v[168:169]
	v_cvt_pk_f16_f32 v133, v92, v93
	v_cvt_pk_f16_f32 v132, v90, v91
	v_cvt_pk_f16_f32 v131, v96, v97
	v_cvt_pk_f16_f32 v130, v94, v95
	v_lshl_add_u64 v[134:135], v[134:135], 0, v[158:159]
	global_store_dwordx4 v[134:135], v[130:133], off
	v_cvt_f32_f16_e32 v136, v147
	v_cvt_f32_f16_sdwa v137, v147 dst_sel:DWORD dst_unused:UNUSED_PAD src0_sel:WORD_1
	v_cvt_f32_f16_e32 v130, v149
	v_cvt_f32_f16_sdwa v131, v149 dst_sel:DWORD dst_unused:UNUSED_PAD src0_sel:WORD_1
	v_cvt_f32_f16_e32 v132, v148
	v_cvt_f32_f16_sdwa v133, v148 dst_sel:DWORD dst_unused:UNUSED_PAD src0_sel:WORD_1
	v_cvt_f32_f16_e32 v148, v146
	v_cvt_f32_f16_sdwa v149, v146 dst_sel:DWORD dst_unused:UNUSED_PAD src0_sel:WORD_1
	v_pk_add_f32 v[88:89], v[88:89], v[136:137]
	v_pk_add_f32 v[82:83], v[82:83], v[132:133]
	v_pk_add_f32 v[84:85], v[84:85], v[130:131]
	v_pk_add_f32 v[86:87], v[86:87], v[148:149]
	v_cvt_pk_f16_f32 v133, v84, v85
	v_cvt_pk_f16_f32 v132, v82, v83
	v_cvt_pk_f16_f32 v131, v88, v89
	v_cvt_pk_f16_f32 v130, v86, v87
	global_store_dwordx4 v[134:135], v[130:133], off offset:256
	v_cvt_f32_f16_e32 v134, v143
	v_cvt_f32_f16_sdwa v135, v143 dst_sel:DWORD dst_unused:UNUSED_PAD src0_sel:WORD_1
	v_cvt_f32_f16_e32 v130, v145
	v_cvt_f32_f16_sdwa v131, v145 dst_sel:DWORD dst_unused:UNUSED_PAD src0_sel:WORD_1
	v_cvt_f32_f16_e32 v132, v144
	v_cvt_f32_f16_sdwa v133, v144 dst_sel:DWORD dst_unused:UNUSED_PAD src0_sel:WORD_1
	v_cvt_f32_f16_e32 v136, v142
	v_cvt_f32_f16_sdwa v137, v142 dst_sel:DWORD dst_unused:UNUSED_PAD src0_sel:WORD_1
	v_pk_add_f32 v[80:81], v[80:81], v[134:135]
	v_pk_add_f32 v[74:75], v[74:75], v[132:133]
	v_pk_add_f32 v[76:77], v[76:77], v[130:131]
	v_pk_add_f32 v[78:79], v[78:79], v[136:137]
	v_lshl_add_u64 v[134:135], s[4:5], 0, v[166:167]
	v_cvt_pk_f16_f32 v133, v76, v77
	v_cvt_pk_f16_f32 v132, v74, v75
	v_cvt_pk_f16_f32 v131, v80, v81
	v_cvt_pk_f16_f32 v130, v78, v79
	v_lshl_add_u64 v[134:135], v[134:135], 0, v[158:159]
	global_store_dwordx4 v[134:135], v[130:133], off
	v_cvt_f32_f16_e32 v136, v139
	v_cvt_f32_f16_sdwa v137, v139 dst_sel:DWORD dst_unused:UNUSED_PAD src0_sel:WORD_1
	v_cvt_f32_f16_e32 v130, v141
	v_cvt_f32_f16_sdwa v131, v141 dst_sel:DWORD dst_unused:UNUSED_PAD src0_sel:WORD_1
	v_cvt_f32_f16_e32 v132, v140
	v_cvt_f32_f16_sdwa v133, v140 dst_sel:DWORD dst_unused:UNUSED_PAD src0_sel:WORD_1
	v_cvt_f32_f16_e32 v140, v138
	v_cvt_f32_f16_sdwa v141, v138 dst_sel:DWORD dst_unused:UNUSED_PAD src0_sel:WORD_1
	v_pk_add_f32 v[72:73], v[72:73], v[136:137]
	v_pk_add_f32 v[66:67], v[66:67], v[132:133]
	v_pk_add_f32 v[68:69], v[68:69], v[130:131]
	v_pk_add_f32 v[70:71], v[70:71], v[140:141]
	v_cvt_pk_f16_f32 v133, v68, v69
	v_cvt_pk_f16_f32 v132, v66, v67
	v_cvt_pk_f16_f32 v131, v72, v73
	v_cvt_pk_f16_f32 v130, v70, v71
	global_store_dwordx4 v[134:135], v[130:133], off offset:256
	s_nop 1
	v_add_u32_e32 v130, 0x80, v162
	v_ashrrev_i32_e32 v131, 31, v130
	v_lshlrev_b64 v[170:171], 12, v[130:131]
	v_lshl_add_u64 v[130:131], v[164:165], 0, v[170:171]
	global_load_dwordx4 v[150:153], v[130:131], off
	global_load_dwordx4 v[154:157], v[130:131], off offset:256
	v_add_u32_e32 v130, 0x90, v162
	v_ashrrev_i32_e32 v131, 31, v130
	v_lshlrev_b64 v[180:181], 12, v[130:131]
	v_lshl_add_u64 v[130:131], v[164:165], 0, v[180:181]
	global_load_dwordx4 v[166:169], v[130:131], off
	global_load_dwordx4 v[176:179], v[130:131], off offset:256
	v_add_u32_e32 v130, 0xa0, v162
	v_ashrrev_i32_e32 v131, 31, v130
	v_lshlrev_b64 v[148:149], 12, v[130:131]
	v_lshl_add_u64 v[130:131], v[164:165], 0, v[148:149]
	global_load_dwordx4 v[142:145], v[130:131], off
	global_load_dwordx4 v[138:141], v[130:131], off offset:256
	v_add_u32_e32 v130, 0xb0, v162
	v_ashrrev_i32_e32 v131, 31, v130
	v_lshlrev_b64 v[146:147], 12, v[130:131]
	v_lshl_add_u64 v[130:131], v[164:165], 0, v[146:147]
	global_load_dwordx4 v[134:137], v[130:131], off
	s_nop 0
	global_load_dwordx4 v[130:133], v[130:131], off offset:256
	v_lshl_add_u64 v[148:149], s[4:5], 0, v[148:149]
	v_lshl_add_u64 v[148:149], v[148:149], 0, v[158:159]
	s_waitcnt vmcnt(7)
	v_cvt_f32_f16_e32 v162, v153
	v_cvt_f32_f16_sdwa v163, v153 dst_sel:DWORD dst_unused:UNUSED_PAD src0_sel:WORD_1
	v_cvt_f32_f16_e32 v164, v152
	v_cvt_f32_f16_sdwa v165, v152 dst_sel:DWORD dst_unused:UNUSED_PAD src0_sel:WORD_1
	v_cvt_f32_f16_e32 v152, v151
	v_cvt_f32_f16_sdwa v153, v151 dst_sel:DWORD dst_unused:UNUSED_PAD src0_sel:WORD_1
	v_cvt_f32_f16_e32 v182, v150
	v_cvt_f32_f16_sdwa v183, v150 dst_sel:DWORD dst_unused:UNUSED_PAD src0_sel:WORD_1
	v_pk_add_f32 v[58:59], v[58:59], v[164:165]
	v_pk_add_f32 v[64:65], v[64:65], v[152:153]
	v_pk_add_f32 v[60:61], v[60:61], v[162:163]
	v_pk_add_f32 v[62:63], v[62:63], v[182:183]
	v_lshl_add_u64 v[162:163], s[4:5], 0, v[170:171]
	v_cvt_pk_f16_f32 v153, v60, v61
	v_cvt_pk_f16_f32 v152, v58, v59
	v_cvt_pk_f16_f32 v151, v64, v65
	v_cvt_pk_f16_f32 v150, v62, v63
	v_lshl_add_u64 v[162:163], v[162:163], 0, v[158:159]
	global_store_dwordx4 v[162:163], v[150:153], off
	s_waitcnt vmcnt(7)
	v_cvt_f32_f16_e32 v164, v154
	v_cvt_f32_f16_sdwa v165, v154 dst_sel:DWORD dst_unused:UNUSED_PAD src0_sel:WORD_1
	v_cvt_f32_f16_e32 v150, v157
	v_cvt_f32_f16_sdwa v151, v157 dst_sel:DWORD dst_unused:UNUSED_PAD src0_sel:WORD_1
	v_cvt_f32_f16_e32 v152, v156
	v_cvt_f32_f16_sdwa v153, v156 dst_sel:DWORD dst_unused:UNUSED_PAD src0_sel:WORD_1
	v_cvt_f32_f16_e32 v156, v155
	v_cvt_f32_f16_sdwa v157, v155 dst_sel:DWORD dst_unused:UNUSED_PAD src0_sel:WORD_1
	v_pk_add_f32 v[54:55], v[54:55], v[164:165]
	v_pk_add_f32 v[50:51], v[50:51], v[152:153]
	v_pk_add_f32 v[52:53], v[52:53], v[150:151]
	v_pk_add_f32 v[56:57], v[56:57], v[156:157]
	v_cvt_pk_f16_f32 v153, v52, v53
	v_cvt_pk_f16_f32 v152, v50, v51
	v_cvt_pk_f16_f32 v151, v56, v57
	v_cvt_pk_f16_f32 v150, v54, v55
	global_store_dwordx4 v[162:163], v[150:153], off offset:256
	s_waitcnt vmcnt(7)
; __device__ __forceinline__ float bf_lo(unsigned w) { return __uint_as_float(w << 16); }
; __device__ __forceinline__ float bf_hi(unsigned w) { return __uint_as_float(w & 0xffff0000u); }
; __device__ __forceinline__ float sigmoidf_fast(float x) { return __builtin_amdgcn_rcpf(1.0f + __expf(-x)); }
;     __device__ __forceinline__ void run(const f32x4 (&v)[2][2][4][2], const Unit& u, int wr, int wc, int fr, int fq, PG8_LAS unsigned char* lds, int wid, int lane, float inv_n, float eps) const {
;     ...
;                 float s = 0.f;
; #pragma unroll
;                 for (int bj = 0; bj < 2; ++bj)
; #pragma unroll
;                     for (int n = 0; n < 2; ++n) { const f32x4 x = v[ai][bj][m][n]; s += (x[0] * x[0] + x[1] * x[1]) + (x[2] * x[2] + x[3] * x[3]); }
;                 s += __shfl_xor(s, 16); s += __shfl_xor(s, 32);
;                 if (fq == 0) P[(ai * HALF + wr * 64 + m * 16 + fr) * 4 + wc] = s;
;     __device__ __forceinline__ void fused(f32x4 (&acc)[2][2][4][2], const Unit& u, int wr, int wc, int fr, int fq, PG8_LAS unsigned char* lds, int wid, int lane) const {
;     ...
;             for (int m = 0; m < 4; ++m) { const size_t off = (size_t)(u.pm * BM + ai * HALF + wr * 64 + m * 16 + fr) * ld + col0;
; #pragma unroll
;                 for (int bj = 0; bj < 2; ++bj) { const f32x8 hv = __builtin_convertvector(hraw[m][bj], f32x8); f32x8 r8;
; #pragma unroll
;                     for (int n = 0; n < 2; ++n) { f32x4 r; const f32x4 a = acc[ai][bj][m][n];
;                         if (MODE == 0) { r[0] = hv[4 * n] + a[0]; r[1] = hv[4 * n + 1] + a[1]; r[2] = hv[4 * n + 2] + a[2]; r[3] = hv[4 * n + 3] + a[3]; }
;                         else { const unsigned e0 = n ? eraw[m][bj].z : eraw[m][bj].x, e1 = n ? eraw[m][bj].w : eraw[m][bj].y;
;                             r[0] = hv[4 * n] + sigmoidf_fast(a[0]) * bf_lo(e0); r[1] = hv[4 * n + 1] + sigmoidf_fast(a[1]) * bf_hi(e0); r[2] = hv[4 * n + 2] + sigmoidf_fast(a[2]) * bf_lo(e1); r[3] = hv[4 * n + 3] + sigmoidf_fast(a[3]) * bf_hi(e1); }
;                         acc[ai][bj][m][n] = r; r8[4 * n] = r[0]; r8[4 * n + 1] = r[1]; r8[4 * n + 2] = r[2]; r8[4 * n + 3] = r[3]; }
;                     *(h16x8*)(H + off + bj * HALF) = __builtin_convertvector(r8, h16x8); }
;                 asm volatile("" : "+v"(acc[ai][0][m][0]), "+v"(acc[ai][0][m][1]), "+v"(acc[ai][1][m][0]), "+v"(acc[ai][1][m][1])); }
	v_cvt_f32_f16_e32 v154, v167
	v_cvt_f32_f16_sdwa v155, v167 dst_sel:DWORD dst_unused:UNUSED_PAD src0_sel:WORD_1
	v_cvt_f32_f16_e32 v150, v169
	v_cvt_f32_f16_sdwa v151, v169 dst_sel:DWORD dst_unused:UNUSED_PAD src0_sel:WORD_1
	v_cvt_f32_f16_e32 v152, v168
	v_cvt_f32_f16_sdwa v153, v168 dst_sel:DWORD dst_unused:UNUSED_PAD src0_sel:WORD_1
	v_cvt_f32_f16_e32 v156, v166
	v_cvt_f32_f16_sdwa v157, v166 dst_sel:DWORD dst_unused:UNUSED_PAD src0_sel:WORD_1
	v_pk_add_f32 v[48:49], v[48:49], v[154:155]
	v_pk_add_f32 v[42:43], v[42:43], v[152:153]
	v_pk_add_f32 v[44:45], v[44:45], v[150:151]
	v_pk_add_f32 v[46:47], v[46:47], v[156:157]
	v_lshl_add_u64 v[154:155], s[4:5], 0, v[180:181]
	v_cvt_pk_f16_f32 v153, v44, v45
	v_cvt_pk_f16_f32 v152, v42, v43
	v_cvt_pk_f16_f32 v151, v48, v49
	v_cvt_pk_f16_f32 v150, v46, v47
	v_lshl_add_u64 v[154:155], v[154:155], 0, v[158:159]
	global_store_dwordx4 v[154:155], v[150:153], off
	s_waitcnt vmcnt(7)
	v_cvt_f32_f16_e32 v156, v177
	v_cvt_f32_f16_sdwa v157, v177 dst_sel:DWORD dst_unused:UNUSED_PAD src0_sel:WORD_1
	v_cvt_f32_f16_e32 v150, v179
	v_cvt_f32_f16_sdwa v151, v179 dst_sel:DWORD dst_unused:UNUSED_PAD src0_sel:WORD_1
	v_cvt_f32_f16_e32 v152, v178
	v_cvt_f32_f16_sdwa v153, v178 dst_sel:DWORD dst_unused:UNUSED_PAD src0_sel:WORD_1
	v_cvt_f32_f16_e32 v162, v176
	v_cvt_f32_f16_sdwa v163, v176 dst_sel:DWORD dst_unused:UNUSED_PAD src0_sel:WORD_1
	v_pk_add_f32 v[40:41], v[40:41], v[156:157]
	v_pk_add_f32 v[34:35], v[34:35], v[152:153]
	v_pk_add_f32 v[36:37], v[36:37], v[150:151]
	v_pk_add_f32 v[38:39], v[38:39], v[162:163]
	v_cvt_pk_f16_f32 v153, v36, v37
	v_cvt_pk_f16_f32 v152, v34, v35
	v_cvt_pk_f16_f32 v151, v40, v41
	v_cvt_pk_f16_f32 v150, v38, v39
	global_store_dwordx4 v[154:155], v[150:153], off offset:256
	s_waitcnt vmcnt(7)
	v_cvt_f32_f16_e32 v154, v142
	v_cvt_f32_f16_sdwa v155, v142 dst_sel:DWORD dst_unused:UNUSED_PAD src0_sel:WORD_1
	v_cvt_f32_f16_e32 v150, v145
	v_cvt_f32_f16_sdwa v151, v145 dst_sel:DWORD dst_unused:UNUSED_PAD src0_sel:WORD_1
	v_cvt_f32_f16_e32 v152, v144
	v_cvt_f32_f16_sdwa v153, v144 dst_sel:DWORD dst_unused:UNUSED_PAD src0_sel:WORD_1
	v_cvt_f32_f16_e32 v144, v143
	v_cvt_f32_f16_sdwa v145, v143 dst_sel:DWORD dst_unused:UNUSED_PAD src0_sel:WORD_1
	v_pk_add_f32 v[28:29], v[28:29], v[154:155]
	v_pk_add_f32 v[24:25], v[24:25], v[152:153]
	v_pk_add_f32 v[26:27], v[26:27], v[150:151]
	v_pk_add_f32 v[30:31], v[30:31], v[144:145]
	v_cvt_pk_f16_f32 v145, v26, v27
	v_cvt_pk_f16_f32 v144, v24, v25
	v_cvt_pk_f16_f32 v143, v30, v31
	v_cvt_pk_f16_f32 v142, v28, v29
	global_store_dwordx4 v[148:149], v[142:145], off
	s_waitcnt vmcnt(7)
	v_cvt_f32_f16_e32 v150, v138
	v_cvt_f32_f16_sdwa v151, v138 dst_sel:DWORD dst_unused:UNUSED_PAD src0_sel:WORD_1
	v_cvt_f32_f16_e32 v142, v141
	v_cvt_f32_f16_sdwa v143, v141 dst_sel:DWORD dst_unused:UNUSED_PAD src0_sel:WORD_1
	v_cvt_f32_f16_e32 v144, v140
	v_cvt_f32_f16_sdwa v145, v140 dst_sel:DWORD dst_unused:UNUSED_PAD src0_sel:WORD_1
	v_cvt_f32_f16_e32 v140, v139
	v_cvt_f32_f16_sdwa v141, v139 dst_sel:DWORD dst_unused:UNUSED_PAD src0_sel:WORD_1
	v_pk_add_f32 v[20:21], v[20:21], v[150:151]
	v_pk_add_f32 v[16:17], v[16:17], v[144:145]
	v_pk_add_f32 v[18:19], v[18:19], v[142:143]
	v_pk_add_f32 v[22:23], v[22:23], v[140:141]
	v_cvt_pk_f16_f32 v141, v18, v19
	v_cvt_pk_f16_f32 v140, v16, v17
	v_cvt_pk_f16_f32 v139, v22, v23
	v_cvt_pk_f16_f32 v138, v20, v21
	global_store_dwordx4 v[148:149], v[138:141], off offset:256
	s_waitcnt vmcnt(7)
	v_cvt_f32_f16_e32 v142, v134
	v_cvt_f32_f16_sdwa v143, v134 dst_sel:DWORD dst_unused:UNUSED_PAD src0_sel:WORD_1
	v_cvt_f32_f16_e32 v138, v137
	v_cvt_f32_f16_sdwa v139, v137 dst_sel:DWORD dst_unused:UNUSED_PAD src0_sel:WORD_1
	v_cvt_f32_f16_e32 v140, v136
	v_cvt_f32_f16_sdwa v141, v136 dst_sel:DWORD dst_unused:UNUSED_PAD src0_sel:WORD_1
	v_cvt_f32_f16_e32 v136, v135
	v_cvt_f32_f16_sdwa v137, v135 dst_sel:DWORD dst_unused:UNUSED_PAD src0_sel:WORD_1
	v_pk_add_f32 v[12:13], v[12:13], v[142:143]
	v_pk_add_f32 v[8:9], v[8:9], v[140:141]
	v_pk_add_f32 v[10:11], v[10:11], v[138:139]
	v_pk_add_f32 v[14:15], v[14:15], v[136:137]
	v_lshl_add_u64 v[138:139], s[4:5], 0, v[146:147]
	v_cvt_pk_f16_f32 v137, v10, v11
	v_cvt_pk_f16_f32 v136, v8, v9
	v_cvt_pk_f16_f32 v135, v14, v15
	v_cvt_pk_f16_f32 v134, v12, v13
	v_lshl_add_u64 v[138:139], v[138:139], 0, v[158:159]
	global_store_dwordx4 v[138:139], v[134:137], off
	s_waitcnt vmcnt(7)
	v_cvt_f32_f16_e32 v140, v130
	v_cvt_f32_f16_sdwa v141, v130 dst_sel:DWORD dst_unused:UNUSED_PAD src0_sel:WORD_1
	v_cvt_f32_f16_e32 v134, v133
	v_cvt_f32_f16_sdwa v135, v133 dst_sel:DWORD dst_unused:UNUSED_PAD src0_sel:WORD_1
	v_cvt_f32_f16_e32 v136, v132
	v_cvt_f32_f16_sdwa v137, v132 dst_sel:DWORD dst_unused:UNUSED_PAD src0_sel:WORD_1
	v_cvt_f32_f16_e32 v132, v131
	v_cvt_f32_f16_sdwa v133, v131 dst_sel:DWORD dst_unused:UNUSED_PAD src0_sel:WORD_1
	v_pk_add_f32 v[4:5], v[4:5], v[140:141]
	v_pk_add_f32 v[0:1], v[0:1], v[136:137]
	v_pk_add_f32 v[2:3], v[2:3], v[134:135]
	v_pk_add_f32 v[6:7], v[6:7], v[132:133]
	v_cvt_pk_f16_f32 v133, v2, v3
	v_cvt_pk_f16_f32 v132, v0, v1
	v_cvt_pk_f16_f32 v131, v6, v7
	v_cvt_pk_f16_f32 v130, v4, v5
	global_store_dwordx4 v[138:139], v[130:133], off offset:256
	v_mul_f32_e32 v134, v117, v117
	v_fmac_f32_e32 v134, v116, v116
	v_and_b32_e32 v131, 64, v236
	v_xor_b32_e32 v130, 16, v236
	v_add_u32_e32 v131, 64, v131
	v_cmp_lt_i32_e32 vcc, v130, v131
	v_xor_b32_e32 v132, 32, v236
	v_mul_f32_e32 v133, v121, v121
	v_cndmask_b32_e32 v130, v236, v130, vcc
	v_cmp_lt_i32_e32 vcc, v132, v131
	v_fmac_f32_e32 v133, v120, v120
	v_lshlrev_b32_e32 v130, 2, v130
	v_cndmask_b32_e32 v131, v236, v132, vcc
	v_mul_f32_e32 v132, v119, v119
	v_fmac_f32_e32 v132, v118, v118
	v_add_f32_e32 v132, v132, v133
	v_mul_f32_e32 v133, v115, v115
	v_fmac_f32_e32 v133, v114, v114
	v_add_f32_e32 v133, v133, v134
	v_add_f32_e32 v132, v132, v133
	v_mul_f32_e32 v133, v127, v127
	v_mul_f32_e32 v134, v129, v129
	v_fmac_f32_e32 v133, v126, v126
	v_fmac_f32_e32 v134, v128, v128
	v_add_f32_e32 v133, v133, v134
	v_add_f32_e32 v132, v133, v132
	v_mul_f32_e32 v133, v123, v123
	v_mul_f32_e32 v134, v125, v125
	v_fmac_f32_e32 v133, v122, v122
	v_fmac_f32_e32 v134, v124, v124
	v_add_f32_e32 v133, v133, v134
	v_add_f32_e32 v132, v133, v132
	ds_bpermute_b32 v133, v130, v132
	v_lshlrev_b32_e32 v131, 2, v131
	s_lshl_b32 s4, s36, 2
	s_waitcnt lgkmcnt(0)
	v_add_f32_e32 v132, v132, v133
	ds_bpermute_b32 v133, v131, v132
	v_cmp_gt_u32_e32 vcc, 16, v32
	s_add_i32 s10, s4, 0
	s_and_saveexec_b64 s[4:5], vcc
	s_cbranch_execz .LBB0_957
	s_lshl_b32 s11, s20, 10
	s_add_i32 s11, s10, s11
	v_lshl_add_u32 v134, v174, 4, s11
	s_waitcnt lgkmcnt(0)
	v_add_f32_e32 v132, v132, v133
	ds_write_b32 v134, v132

; __device__ __forceinline__ float bf_lo(unsigned w) { return __uint_as_float(w << 16); }
; #define PG8_BAR __builtin_amdgcn_s_barrier()
;     __device__ __forceinline__ void fused(f32x4 (&acc)[2][2][4][2], const Unit& u, int wr, int wc, int fr, int fq, PG8_LAS unsigned char* lds, int wid, int lane) const {
;     ...
;         for (int ai = 0; ai < 2; ++ai) {
;             h16x8 hraw[4][2]; u32x4 eraw[4][2];
; #pragma unroll
;             for (int m = 0; m < 4; ++m) { const size_t off = (size_t)(u.pm * BM + ai * HALF + wr * 64 + m * 16 + fr) * ld + col0;
; #pragma unroll
;                 for (int bj = 0; bj < 2; ++bj) { hraw[m][bj] = *(const h16x8*)(H + off + bj * HALF); if (MODE != 0) eraw[m][bj] = *(const u32x4*)(E + off + bj * HALF); } }
; #pragma unroll
;             for (int m = 0; m < 4; ++m) { const size_t off = (size_t)(u.pm * BM + ai * HALF + wr * 64 + m * 16 + fr) * ld + col0;
; #pragma unroll
;                 for (int bj = 0; bj < 2; ++bj) { const f32x8 hv = __builtin_convertvector(hraw[m][bj], f32x8); f32x8 r8;
; #pragma unroll
;                     for (int n = 0; n < 2; ++n) { f32x4 r; const f32x4 a = acc[ai][bj][m][n];
;                         if (MODE == 0) { r[0] = hv[4 * n] + a[0]; r[1] = hv[4 * n + 1] + a[1]; r[2] = hv[4 * n + 2] + a[2]; r[3] = hv[4 * n + 3] + a[3]; }
;                         else { const unsigned e0 = n ? eraw[m][bj].z : eraw[m][bj].x, e1 = n ? eraw[m][bj].w : eraw[m][bj].y;
;                             r[0] = hv[4 * n] + sigmoidf_fast(a[0]) * bf_lo(e0); r[1] = hv[4 * n + 1] + sigmoidf_fast(a[1]) * bf_hi(e0); r[2] = hv[4 * n + 2] + sigmoidf_fast(a[2]) * bf_lo(e1); r[3] = hv[4 * n + 3] + sigmoidf_fast(a[3]) * bf_hi(e1); }
;                         acc[ai][bj][m][n] = r; r8[4 * n] = r[0]; r8[4 * n + 1] = r[1]; r8[4 * n + 2] = r[2]; r8[4 * n + 3] = r[3]; }
;                     *(h16x8*)(H + off + bj * HALF) = __builtin_convertvector(r8, h16x8); }
;                 asm volatile("" : "+v"(acc[ai][0][m][0]), "+v"(acc[ai][0][m][1]), "+v"(acc[ai][1][m][0]), "+v"(acc[ai][1][m][1])); }
; template <class Epi, class Sched, bool ALIGN_EPI = false, bool SP2 = false, bool KHOOK = false>
; __device__ __forceinline__ void gemm_phase(PG8_LAS unsigned char* lds, const Gemm g, const Sched& S, const Epi& E, const int tid_in) {
;     ...
;     PG8_WAIT_V(0);
;     if constexpr (!ALIGN_EPI) { if (wr == 0) PG8_BAR; }
;     PG8_BAR;
.LBB0_1175:
	s_lshl_b32 s4, s36, 5
	s_lshl_b32 s5, s0, 8
	v_lshrrev_b32_e32 v122, 1, v173
	s_or_b32 s4, s5, s4
	s_lshl_b32 s22, s33, 8
	v_and_or_b32 v160, v122, 24, s4
	s_add_i32 s4, s22, s45
	v_or_b32_e32 v162, s4, v174
	v_ashrrev_i32_e32 v161, 31, v160
	v_readlane_b32 s4, v252, 57
	v_lshlrev_b64 v[158:159], 1, v[160:161]
	v_readlane_b32 s5, v252, 58
	v_ashrrev_i32_e32 v163, 31, v162
	v_lshlrev_b64 v[180:181], 12, v[162:163]
	v_lshl_add_u64 v[164:165], s[4:5], 0, v[158:159]
	v_lshl_add_u64 v[126:127], v[164:165], 0, v[180:181]
	global_load_dwordx4 v[122:125], v[126:127], off
	s_nop 0
	global_load_dwordx4 v[126:129], v[126:127], off offset:256
	v_or_b32_e32 v138, 16, v162
	v_ashrrev_i32_e32 v139, 31, v138
	v_lshlrev_b64 v[170:171], 12, v[138:139]
	v_lshl_add_u64 v[138:139], v[164:165], 0, v[170:171]
	global_load_dwordx4 v[176:179], v[138:139], off
	global_load_dwordx4 v[154:157], v[138:139], off offset:256
	v_or_b32_e32 v138, 32, v162
	v_ashrrev_i32_e32 v139, 31, v138
	v_lshlrev_b64 v[168:169], 12, v[138:139]
	v_lshl_add_u64 v[138:139], v[164:165], 0, v[168:169]
	global_load_dwordx4 v[150:153], v[138:139], off
	global_load_dwordx4 v[146:149], v[138:139], off offset:256
	v_or_b32_e32 v138, 48, v162
	v_ashrrev_i32_e32 v139, 31, v138
	v_lshlrev_b64 v[166:167], 12, v[138:139]
	v_lshl_add_u64 v[138:139], v[164:165], 0, v[166:167]
	global_load_dwordx4 v[142:145], v[138:139], off
	s_nop 0
	global_load_dwordx4 v[138:141], v[138:139], off offset:256
	s_waitcnt vmcnt(0)
	s_cmpk_gt_u32 s2, 0xff
	s_cbranch_scc1 .LBB0_1177
	s_barrier
.LBB0_1177:
	s_barrier
	v_lshl_add_u64 v[180:181], s[4:5], 0, v[180:181]
	v_lshl_add_u64 v[180:181], v[180:181], 0, v[158:159]
	v_and_b32_e32 v32, 63, v173
	s_waitcnt vmcnt(0)
	v_cvt_f32_f16_e32 v182, v125
	v_cvt_f32_f16_sdwa v183, v125 dst_sel:DWORD dst_unused:UNUSED_PAD src0_sel:WORD_1
	v_cvt_f32_f16_e32 v184, v124
	v_cvt_f32_f16_sdwa v185, v124 dst_sel:DWORD dst_unused:UNUSED_PAD src0_sel:WORD_1
	v_cvt_f32_f16_e32 v124, v123
	v_cvt_f32_f16_sdwa v125, v123 dst_sel:DWORD dst_unused:UNUSED_PAD src0_sel:WORD_1
	v_cvt_f32_f16_e32 v186, v122
	v_cvt_f32_f16_sdwa v187, v122 dst_sel:DWORD dst_unused:UNUSED_PAD src0_sel:WORD_1
	v_pk_add_f32 v[114:115], v[114:115], v[184:185]
	v_pk_add_f32 v[120:121], v[120:121], v[124:125]
	v_pk_add_f32 v[116:117], v[116:117], v[182:183]
	v_pk_add_f32 v[118:119], v[118:119], v[186:187]
	v_cvt_pk_f16_f32 v125, v116, v117
	v_cvt_pk_f16_f32 v124, v114, v115
	v_cvt_pk_f16_f32 v123, v120, v121
	v_cvt_pk_f16_f32 v122, v118, v119
	global_store_dwordx4 v[180:181], v[122:125], off
	v_cvt_f32_f16_e32 v182, v126
	v_cvt_f32_f16_sdwa v183, v126 dst_sel:DWORD dst_unused:UNUSED_PAD src0_sel:WORD_1
	v_cvt_f32_f16_e32 v124, v129
	v_cvt_f32_f16_sdwa v125, v129 dst_sel:DWORD dst_unused:UNUSED_PAD src0_sel:WORD_1
	v_cvt_f32_f16_e32 v122, v128
	v_cvt_f32_f16_sdwa v123, v128 dst_sel:DWORD dst_unused:UNUSED_PAD src0_sel:WORD_1
	v_cvt_f32_f16_e32 v128, v127
	v_cvt_f32_f16_sdwa v129, v127 dst_sel:DWORD dst_unused:UNUSED_PAD src0_sel:WORD_1
	v_pk_add_f32 v[126:127], v[102:103], v[182:183]
	v_pk_add_f32 v[122:123], v[98:99], v[122:123]
	v_pk_add_f32 v[124:125], v[100:101], v[124:125]
	v_pk_add_f32 v[128:129], v[104:105], v[128:129]
	v_cvt_pk_f16_f32 v101, v124, v125
	v_cvt_pk_f16_f32 v100, v122, v123
	v_cvt_pk_f16_f32 v99, v128, v129
	v_cvt_pk_f16_f32 v98, v126, v127
	global_store_dwordx4 v[180:181], v[98:101], off offset:256
	v_cvt_f32_f16_e32 v104, v177
	v_cvt_f32_f16_sdwa v105, v177 dst_sel:DWORD dst_unused:UNUSED_PAD src0_sel:WORD_1
	v_cvt_f32_f16_e32 v100, v179
	v_cvt_f32_f16_sdwa v101, v179 dst_sel:DWORD dst_unused:UNUSED_PAD src0_sel:WORD_1
	v_cvt_f32_f16_e32 v98, v178
	v_cvt_f32_f16_sdwa v99, v178 dst_sel:DWORD dst_unused:UNUSED_PAD src0_sel:WORD_1
	v_cvt_f32_f16_e32 v102, v176
	v_cvt_f32_f16_sdwa v103, v176 dst_sel:DWORD dst_unused:UNUSED_PAD src0_sel:WORD_1
	v_pk_add_f32 v[104:105], v[136:137], v[104:105]
	v_pk_add_f32 v[98:99], v[130:131], v[98:99]
	v_pk_add_f32 v[100:101], v[132:133], v[100:101]
	v_pk_add_f32 v[102:103], v[134:135], v[102:103]
	v_lshl_add_u64 v[130:131], s[4:5], 0, v[170:171]
	v_cvt_pk_f16_f32 v135, v100, v101
	v_cvt_pk_f16_f32 v134, v98, v99
	v_cvt_pk_f16_f32 v133, v104, v105
	v_cvt_pk_f16_f32 v132, v102, v103
	v_lshl_add_u64 v[130:131], v[130:131], 0, v[158:159]
	global_store_dwordx4 v[130:131], v[132:135], off
	v_cvt_f32_f16_e32 v136, v155
	v_cvt_f32_f16_sdwa v137, v155 dst_sel:DWORD dst_unused:UNUSED_PAD src0_sel:WORD_1
	v_cvt_f32_f16_e32 v132, v157
	v_cvt_f32_f16_sdwa v133, v157 dst_sel:DWORD dst_unused:UNUSED_PAD src0_sel:WORD_1
	v_cvt_f32_f16_e32 v134, v156
	v_cvt_f32_f16_sdwa v135, v156 dst_sel:DWORD dst_unused:UNUSED_PAD src0_sel:WORD_1
	v_cvt_f32_f16_e32 v156, v154
	v_cvt_f32_f16_sdwa v157, v154 dst_sel:DWORD dst_unused:UNUSED_PAD src0_sel:WORD_1
	v_pk_add_f32 v[112:113], v[112:113], v[136:137]
	v_pk_add_f32 v[106:107], v[106:107], v[134:135]
	v_pk_add_f32 v[108:109], v[108:109], v[132:133]
	v_pk_add_f32 v[110:111], v[110:111], v[156:157]
	v_cvt_pk_f16_f32 v135, v108, v109
	v_cvt_pk_f16_f32 v134, v106, v107
	v_cvt_pk_f16_f32 v133, v112, v113
	v_cvt_pk_f16_f32 v132, v110, v111
	global_store_dwordx4 v[130:131], v[132:135], off offset:256
	v_cvt_f32_f16_e32 v130, v153
	v_cvt_f32_f16_sdwa v131, v153 dst_sel:DWORD dst_unused:UNUSED_PAD src0_sel:WORD_1
	v_cvt_f32_f16_e32 v132, v152
	v_cvt_f32_f16_sdwa v133, v152 dst_sel:DWORD dst_unused:UNUSED_PAD src0_sel:WORD_1
	v_cvt_f32_f16_e32 v134, v151
	v_cvt_f32_f16_sdwa v135, v151 dst_sel:DWORD dst_unused:UNUSED_PAD src0_sel:WORD_1
	v_cvt_f32_f16_e32 v136, v150
	v_cvt_f32_f16_sdwa v137, v150 dst_sel:DWORD dst_unused:UNUSED_PAD src0_sel:WORD_1
; __device__ __forceinline__ float bf_lo(unsigned w) { return __uint_as_float(w << 16); }
; __device__ __forceinline__ float bf_hi(unsigned w) { return __uint_as_float(w & 0xffff0000u); }
; __device__ __forceinline__ float sigmoidf_fast(float x) { return __builtin_amdgcn_rcpf(1.0f + __expf(-x)); }
;     __device__ __forceinline__ void fused(f32x4 (&acc)[2][2][4][2], const Unit& u, int wr, int wc, int fr, int fq, PG8_LAS unsigned char* lds, int wid, int lane) const {
;     ...
;             for (int m = 0; m < 4; ++m) { const size_t off = (size_t)(u.pm * BM + ai * HALF + wr * 64 + m * 16 + fr) * ld + col0;
; #pragma unroll
;                 for (int bj = 0; bj < 2; ++bj) { hraw[m][bj] = *(const h16x8*)(H + off + bj * HALF); if (MODE != 0) eraw[m][bj] = *(const u32x4*)(E + off + bj * HALF); } }
; #pragma unroll
;             for (int m = 0; m < 4; ++m) { const size_t off = (size_t)(u.pm * BM + ai * HALF + wr * 64 + m * 16 + fr) * ld + col0;
; #pragma unroll
;                 for (int bj = 0; bj < 2; ++bj) { const f32x8 hv = __builtin_convertvector(hraw[m][bj], f32x8); f32x8 r8;
; #pragma unroll
;                     for (int n = 0; n < 2; ++n) { f32x4 r; const f32x4 a = acc[ai][bj][m][n];
;                         if (MODE == 0) { r[0] = hv[4 * n] + a[0]; r[1] = hv[4 * n + 1] + a[1]; r[2] = hv[4 * n + 2] + a[2]; r[3] = hv[4 * n + 3] + a[3]; }
;                         else { const unsigned e0 = n ? eraw[m][bj].z : eraw[m][bj].x, e1 = n ? eraw[m][bj].w : eraw[m][bj].y;
;                             r[0] = hv[4 * n] + sigmoidf_fast(a[0]) * bf_lo(e0); r[1] = hv[4 * n + 1] + sigmoidf_fast(a[1]) * bf_hi(e0); r[2] = hv[4 * n + 2] + sigmoidf_fast(a[2]) * bf_lo(e1); r[3] = hv[4 * n + 3] + sigmoidf_fast(a[3]) * bf_hi(e1); }
;                         acc[ai][bj][m][n] = r; r8[4 * n] = r[0]; r8[4 * n + 1] = r[1]; r8[4 * n + 2] = r[2]; r8[4 * n + 3] = r[3]; }
;                     *(h16x8*)(H + off + bj * HALF) = __builtin_convertvector(r8, h16x8); }
;                 asm volatile("" : "+v"(acc[ai][0][m][0]), "+v"(acc[ai][0][m][1]), "+v"(acc[ai][1][m][0]), "+v"(acc[ai][1][m][1])); }
	v_pk_add_f32 v[90:91], v[90:91], v[132:133]
	v_pk_add_f32 v[96:97], v[96:97], v[134:135]
	v_pk_add_f32 v[92:93], v[92:93], v[130:131]
	v_pk_add_f32 v[94:95], v[94:95], v[136:137]
	v_lshl_add_u64 v[134:135], s[4:5], 0, v[168:169]
	v_cvt_pk_f16_f32 v133, v92, v93
	v_cvt_pk_f16_f32 v132, v90, v91
	v_cvt_pk_f16_f32 v131, v96, v97
	v_cvt_pk_f16_f32 v130, v94, v95
	v_lshl_add_u64 v[134:135], v[134:135], 0, v[158:159]
	global_store_dwordx4 v[134:135], v[130:133], off
	v_cvt_f32_f16_e32 v136, v147
	v_cvt_f32_f16_sdwa v137, v147 dst_sel:DWORD dst_unused:UNUSED_PAD src0_sel:WORD_1
	v_cvt_f32_f16_e32 v130, v149
	v_cvt_f32_f16_sdwa v131, v149 dst_sel:DWORD dst_unused:UNUSED_PAD src0_sel:WORD_1
	v_cvt_f32_f16_e32 v132, v148
	v_cvt_f32_f16_sdwa v133, v148 dst_sel:DWORD dst_unused:UNUSED_PAD src0_sel:WORD_1
	v_cvt_f32_f16_e32 v148, v146
	v_cvt_f32_f16_sdwa v149, v146 dst_sel:DWORD dst_unused:UNUSED_PAD src0_sel:WORD_1
	v_pk_add_f32 v[88:89], v[88:89], v[136:137]
	v_pk_add_f32 v[82:83], v[82:83], v[132:133]
	v_pk_add_f32 v[84:85], v[84:85], v[130:131]
	v_pk_add_f32 v[86:87], v[86:87], v[148:149]
	v_cvt_pk_f16_f32 v133, v84, v85
	v_cvt_pk_f16_f32 v132, v82, v83
	v_cvt_pk_f16_f32 v131, v88, v89
	v_cvt_pk_f16_f32 v130, v86, v87
	global_store_dwordx4 v[134:135], v[130:133], off offset:256
	v_cvt_f32_f16_e32 v134, v143
	v_cvt_f32_f16_sdwa v135, v143 dst_sel:DWORD dst_unused:UNUSED_PAD src0_sel:WORD_1
	v_cvt_f32_f16_e32 v130, v145
	v_cvt_f32_f16_sdwa v131, v145 dst_sel:DWORD dst_unused:UNUSED_PAD src0_sel:WORD_1
	v_cvt_f32_f16_e32 v132, v144
	v_cvt_f32_f16_sdwa v133, v144 dst_sel:DWORD dst_unused:UNUSED_PAD src0_sel:WORD_1
	v_cvt_f32_f16_e32 v136, v142
	v_cvt_f32_f16_sdwa v137, v142 dst_sel:DWORD dst_unused:UNUSED_PAD src0_sel:WORD_1
	v_pk_add_f32 v[80:81], v[80:81], v[134:135]
	v_pk_add_f32 v[74:75], v[74:75], v[132:133]
	v_pk_add_f32 v[76:77], v[76:77], v[130:131]
	v_pk_add_f32 v[78:79], v[78:79], v[136:137]
	v_lshl_add_u64 v[134:135], s[4:5], 0, v[166:167]
	v_cvt_pk_f16_f32 v133, v76, v77
	v_cvt_pk_f16_f32 v132, v74, v75
	v_cvt_pk_f16_f32 v131, v80, v81
	v_cvt_pk_f16_f32 v130, v78, v79
	v_lshl_add_u64 v[134:135], v[134:135], 0, v[158:159]
	global_store_dwordx4 v[134:135], v[130:133], off
	v_cvt_f32_f16_e32 v136, v139
	v_cvt_f32_f16_sdwa v137, v139 dst_sel:DWORD dst_unused:UNUSED_PAD src0_sel:WORD_1
	v_cvt_f32_f16_e32 v130, v141
	v_cvt_f32_f16_sdwa v131, v141 dst_sel:DWORD dst_unused:UNUSED_PAD src0_sel:WORD_1
	v_cvt_f32_f16_e32 v132, v140
	v_cvt_f32_f16_sdwa v133, v140 dst_sel:DWORD dst_unused:UNUSED_PAD src0_sel:WORD_1
	v_cvt_f32_f16_e32 v140, v138
	v_cvt_f32_f16_sdwa v141, v138 dst_sel:DWORD dst_unused:UNUSED_PAD src0_sel:WORD_1
	v_pk_add_f32 v[72:73], v[72:73], v[136:137]
	v_pk_add_f32 v[66:67], v[66:67], v[132:133]
	v_pk_add_f32 v[68:69], v[68:69], v[130:131]
	v_pk_add_f32 v[70:71], v[70:71], v[140:141]
	v_cvt_pk_f16_f32 v133, v68, v69
	v_cvt_pk_f16_f32 v132, v66, v67
	v_cvt_pk_f16_f32 v131, v72, v73
	v_cvt_pk_f16_f32 v130, v70, v71
	global_store_dwordx4 v[134:135], v[130:133], off offset:256
	s_nop 1
	v_add_u32_e32 v130, 0x80, v162
	v_ashrrev_i32_e32 v131, 31, v130
	v_lshlrev_b64 v[170:171], 12, v[130:131]
	v_lshl_add_u64 v[130:131], v[164:165], 0, v[170:171]
	global_load_dwordx4 v[150:153], v[130:131], off
	global_load_dwordx4 v[154:157], v[130:131], off offset:256
	v_add_u32_e32 v130, 0x90, v162
	v_ashrrev_i32_e32 v131, 31, v130
	v_lshlrev_b64 v[180:181], 12, v[130:131]
	v_lshl_add_u64 v[130:131], v[164:165], 0, v[180:181]
	global_load_dwordx4 v[166:169], v[130:131], off
	global_load_dwordx4 v[176:179], v[130:131], off offset:256
	v_add_u32_e32 v130, 0xa0, v162
	v_ashrrev_i32_e32 v131, 31, v130
	v_lshlrev_b64 v[148:149], 12, v[130:131]
	v_lshl_add_u64 v[130:131], v[164:165], 0, v[148:149]
	global_load_dwordx4 v[142:145], v[130:131], off
	global_load_dwordx4 v[138:141], v[130:131], off offset:256
	v_add_u32_e32 v130, 0xb0, v162
	v_ashrrev_i32_e32 v131, 31, v130
	v_lshlrev_b64 v[146:147], 12, v[130:131]
	v_lshl_add_u64 v[130:131], v[164:165], 0, v[146:147]
	global_load_dwordx4 v[134:137], v[130:131], off
	s_nop 0
	global_load_dwordx4 v[130:133], v[130:131], off offset:256
	v_lshl_add_u64 v[148:149], s[4:5], 0, v[148:149]
	v_lshl_add_u64 v[148:149], v[148:149], 0, v[158:159]
	s_waitcnt vmcnt(7)
	v_cvt_f32_f16_e32 v162, v153
	v_cvt_f32_f16_sdwa v163, v153 dst_sel:DWORD dst_unused:UNUSED_PAD src0_sel:WORD_1
	v_cvt_f32_f16_e32 v164, v152
	v_cvt_f32_f16_sdwa v165, v152 dst_sel:DWORD dst_unused:UNUSED_PAD src0_sel:WORD_1
	v_cvt_f32_f16_e32 v152, v151
	v_cvt_f32_f16_sdwa v153, v151 dst_sel:DWORD dst_unused:UNUSED_PAD src0_sel:WORD_1
	v_cvt_f32_f16_e32 v182, v150
	v_cvt_f32_f16_sdwa v183, v150 dst_sel:DWORD dst_unused:UNUSED_PAD src0_sel:WORD_1
	v_pk_add_f32 v[58:59], v[58:59], v[164:165]
	v_pk_add_f32 v[64:65], v[64:65], v[152:153]
	v_pk_add_f32 v[60:61], v[60:61], v[162:163]
	v_pk_add_f32 v[62:63], v[62:63], v[182:183]
	v_lshl_add_u64 v[162:163], s[4:5], 0, v[170:171]
	v_cvt_pk_f16_f32 v153, v60, v61
	v_cvt_pk_f16_f32 v152, v58, v59
	v_cvt_pk_f16_f32 v151, v64, v65
	v_cvt_pk_f16_f32 v150, v62, v63
	v_lshl_add_u64 v[162:163], v[162:163], 0, v[158:159]
	global_store_dwordx4 v[162:163], v[150:153], off
	s_waitcnt vmcnt(7)
	v_cvt_f32_f16_e32 v164, v154
	v_cvt_f32_f16_sdwa v165, v154 dst_sel:DWORD dst_unused:UNUSED_PAD src0_sel:WORD_1
	v_cvt_f32_f16_e32 v150, v157
	v_cvt_f32_f16_sdwa v151, v157 dst_sel:DWORD dst_unused:UNUSED_PAD src0_sel:WORD_1
	v_cvt_f32_f16_e32 v152, v156
	v_cvt_f32_f16_sdwa v153, v156 dst_sel:DWORD dst_unused:UNUSED_PAD src0_sel:WORD_1
	v_cvt_f32_f16_e32 v156, v155
	v_cvt_f32_f16_sdwa v157, v155 dst_sel:DWORD dst_unused:UNUSED_PAD src0_sel:WORD_1
	v_pk_add_f32 v[54:55], v[54:55], v[164:165]
	v_pk_add_f32 v[50:51], v[50:51], v[152:153]
	v_pk_add_f32 v[52:53], v[52:53], v[150:151]
	v_pk_add_f32 v[56:57], v[56:57], v[156:157]
	v_cvt_pk_f16_f32 v153, v52, v53
	v_cvt_pk_f16_f32 v152, v50, v51
	v_cvt_pk_f16_f32 v151, v56, v57
	v_cvt_pk_f16_f32 v150, v54, v55
	global_store_dwordx4 v[162:163], v[150:153], off offset:256
	s_waitcnt vmcnt(7)
; __device__ __forceinline__ float bf_lo(unsigned w) { return __uint_as_float(w << 16); }
; __device__ __forceinline__ float bf_hi(unsigned w) { return __uint_as_float(w & 0xffff0000u); }
; __device__ __forceinline__ float sigmoidf_fast(float x) { return __builtin_amdgcn_rcpf(1.0f + __expf(-x)); }
;     __device__ __forceinline__ void run(const f32x4 (&v)[2][2][4][2], const Unit& u, int wr, int wc, int fr, int fq, PG8_LAS unsigned char* lds, int wid, int lane, float inv_n, float eps) const {
;     ...
;                 float s = 0.f;
; #pragma unroll
;                 for (int bj = 0; bj < 2; ++bj)
; #pragma unroll
;                     for (int n = 0; n < 2; ++n) { const f32x4 x = v[ai][bj][m][n]; s += (x[0] * x[0] + x[1] * x[1]) + (x[2] * x[2] + x[3] * x[3]); }
;                 s += __shfl_xor(s, 16); s += __shfl_xor(s, 32);
;                 if (fq == 0) P[(ai * HALF + wr * 64 + m * 16 + fr) * 4 + wc] = s;
;     __device__ __forceinline__ void fused(f32x4 (&acc)[2][2][4][2], const Unit& u, int wr, int wc, int fr, int fq, PG8_LAS unsigned char* lds, int wid, int lane) const {
;     ...
;             for (int m = 0; m < 4; ++m) { const size_t off = (size_t)(u.pm * BM + ai * HALF + wr * 64 + m * 16 + fr) * ld + col0;
; #pragma unroll
;                 for (int bj = 0; bj < 2; ++bj) { const f32x8 hv = __builtin_convertvector(hraw[m][bj], f32x8); f32x8 r8;
; #pragma unroll
;                     for (int n = 0; n < 2; ++n) { f32x4 r; const f32x4 a = acc[ai][bj][m][n];
;                         if (MODE == 0) { r[0] = hv[4 * n] + a[0]; r[1] = hv[4 * n + 1] + a[1]; r[2] = hv[4 * n + 2] + a[2]; r[3] = hv[4 * n + 3] + a[3]; }
;                         else { const unsigned e0 = n ? eraw[m][bj].z : eraw[m][bj].x, e1 = n ? eraw[m][bj].w : eraw[m][bj].y;
;                             r[0] = hv[4 * n] + sigmoidf_fast(a[0]) * bf_lo(e0); r[1] = hv[4 * n + 1] + sigmoidf_fast(a[1]) * bf_hi(e0); r[2] = hv[4 * n + 2] + sigmoidf_fast(a[2]) * bf_lo(e1); r[3] = hv[4 * n + 3] + sigmoidf_fast(a[3]) * bf_hi(e1); }
;                         acc[ai][bj][m][n] = r; r8[4 * n] = r[0]; r8[4 * n + 1] = r[1]; r8[4 * n + 2] = r[2]; r8[4 * n + 3] = r[3]; }
;                     *(h16x8*)(H + off + bj * HALF) = __builtin_convertvector(r8, h16x8); }
;                 asm volatile("" : "+v"(acc[ai][0][m][0]), "+v"(acc[ai][0][m][1]), "+v"(acc[ai][1][m][0]), "+v"(acc[ai][1][m][1])); }
	v_cvt_f32_f16_e32 v154, v167
	v_cvt_f32_f16_sdwa v155, v167 dst_sel:DWORD dst_unused:UNUSED_PAD src0_sel:WORD_1
	v_cvt_f32_f16_e32 v150, v169
	v_cvt_f32_f16_sdwa v151, v169 dst_sel:DWORD dst_unused:UNUSED_PAD src0_sel:WORD_1
	v_cvt_f32_f16_e32 v152, v168
	v_cvt_f32_f16_sdwa v153, v168 dst_sel:DWORD dst_unused:UNUSED_PAD src0_sel:WORD_1
	v_cvt_f32_f16_e32 v156, v166
	v_cvt_f32_f16_sdwa v157, v166 dst_sel:DWORD dst_unused:UNUSED_PAD src0_sel:WORD_1
	v_pk_add_f32 v[48:49], v[48:49], v[154:155]
	v_pk_add_f32 v[42:43], v[42:43], v[152:153]
	v_pk_add_f32 v[44:45], v[44:45], v[150:151]
	v_pk_add_f32 v[46:47], v[46:47], v[156:157]
	v_lshl_add_u64 v[154:155], s[4:5], 0, v[180:181]
	v_cvt_pk_f16_f32 v153, v44, v45
	v_cvt_pk_f16_f32 v152, v42, v43
	v_cvt_pk_f16_f32 v151, v48, v49
	v_cvt_pk_f16_f32 v150, v46, v47
	v_lshl_add_u64 v[154:155], v[154:155], 0, v[158:159]
	global_store_dwordx4 v[154:155], v[150:153], off
	s_waitcnt vmcnt(7)
	v_cvt_f32_f16_e32 v156, v177
	v_cvt_f32_f16_sdwa v157, v177 dst_sel:DWORD dst_unused:UNUSED_PAD src0_sel:WORD_1
	v_cvt_f32_f16_e32 v150, v179
	v_cvt_f32_f16_sdwa v151, v179 dst_sel:DWORD dst_unused:UNUSED_PAD src0_sel:WORD_1
	v_cvt_f32_f16_e32 v152, v178
	v_cvt_f32_f16_sdwa v153, v178 dst_sel:DWORD dst_unused:UNUSED_PAD src0_sel:WORD_1
	v_cvt_f32_f16_e32 v162, v176
	v_cvt_f32_f16_sdwa v163, v176 dst_sel:DWORD dst_unused:UNUSED_PAD src0_sel:WORD_1
	v_pk_add_f32 v[40:41], v[40:41], v[156:157]
	v_pk_add_f32 v[34:35], v[34:35], v[152:153]
	v_pk_add_f32 v[36:37], v[36:37], v[150:151]
	v_pk_add_f32 v[38:39], v[38:39], v[162:163]
	v_cvt_pk_f16_f32 v153, v36, v37
	v_cvt_pk_f16_f32 v152, v34, v35
	v_cvt_pk_f16_f32 v151, v40, v41
	v_cvt_pk_f16_f32 v150, v38, v39
	global_store_dwordx4 v[154:155], v[150:153], off offset:256
	s_waitcnt vmcnt(7)
	v_cvt_f32_f16_e32 v154, v142
	v_cvt_f32_f16_sdwa v155, v142 dst_sel:DWORD dst_unused:UNUSED_PAD src0_sel:WORD_1
	v_cvt_f32_f16_e32 v150, v145
	v_cvt_f32_f16_sdwa v151, v145 dst_sel:DWORD dst_unused:UNUSED_PAD src0_sel:WORD_1
	v_cvt_f32_f16_e32 v152, v144
	v_cvt_f32_f16_sdwa v153, v144 dst_sel:DWORD dst_unused:UNUSED_PAD src0_sel:WORD_1
	v_cvt_f32_f16_e32 v144, v143
	v_cvt_f32_f16_sdwa v145, v143 dst_sel:DWORD dst_unused:UNUSED_PAD src0_sel:WORD_1
	v_pk_add_f32 v[28:29], v[28:29], v[154:155]
	v_pk_add_f32 v[24:25], v[24:25], v[152:153]
	v_pk_add_f32 v[26:27], v[26:27], v[150:151]
	v_pk_add_f32 v[30:31], v[30:31], v[144:145]
	v_cvt_pk_f16_f32 v145, v26, v27
	v_cvt_pk_f16_f32 v144, v24, v25
	v_cvt_pk_f16_f32 v143, v30, v31
	v_cvt_pk_f16_f32 v142, v28, v29
	global_store_dwordx4 v[148:149], v[142:145], off
	s_waitcnt vmcnt(7)
	v_cvt_f32_f16_e32 v150, v138
	v_cvt_f32_f16_sdwa v151, v138 dst_sel:DWORD dst_unused:UNUSED_PAD src0_sel:WORD_1
	v_cvt_f32_f16_e32 v142, v141
	v_cvt_f32_f16_sdwa v143, v141 dst_sel:DWORD dst_unused:UNUSED_PAD src0_sel:WORD_1
	v_cvt_f32_f16_e32 v144, v140
	v_cvt_f32_f16_sdwa v145, v140 dst_sel:DWORD dst_unused:UNUSED_PAD src0_sel:WORD_1
	v_cvt_f32_f16_e32 v140, v139
	v_cvt_f32_f16_sdwa v141, v139 dst_sel:DWORD dst_unused:UNUSED_PAD src0_sel:WORD_1
	v_pk_add_f32 v[20:21], v[20:21], v[150:151]
	v_pk_add_f32 v[16:17], v[16:17], v[144:145]
	v_pk_add_f32 v[18:19], v[18:19], v[142:143]
	v_pk_add_f32 v[22:23], v[22:23], v[140:141]
	v_cvt_pk_f16_f32 v141, v18, v19
	v_cvt_pk_f16_f32 v140, v16, v17
	v_cvt_pk_f16_f32 v139, v22, v23
	v_cvt_pk_f16_f32 v138, v20, v21
	global_store_dwordx4 v[148:149], v[138:141], off offset:256
	s_waitcnt vmcnt(7)
	v_cvt_f32_f16_e32 v142, v134
	v_cvt_f32_f16_sdwa v143, v134 dst_sel:DWORD dst_unused:UNUSED_PAD src0_sel:WORD_1
	v_cvt_f32_f16_e32 v138, v137
	v_cvt_f32_f16_sdwa v139, v137 dst_sel:DWORD dst_unused:UNUSED_PAD src0_sel:WORD_1
	v_cvt_f32_f16_e32 v140, v136
	v_cvt_f32_f16_sdwa v141, v136 dst_sel:DWORD dst_unused:UNUSED_PAD src0_sel:WORD_1
	v_cvt_f32_f16_e32 v136, v135
	v_cvt_f32_f16_sdwa v137, v135 dst_sel:DWORD dst_unused:UNUSED_PAD src0_sel:WORD_1
	v_pk_add_f32 v[12:13], v[12:13], v[142:143]
	v_pk_add_f32 v[8:9], v[8:9], v[140:141]
	v_pk_add_f32 v[10:11], v[10:11], v[138:139]
	v_pk_add_f32 v[14:15], v[14:15], v[136:137]
	v_lshl_add_u64 v[138:139], s[4:5], 0, v[146:147]
	v_cvt_pk_f16_f32 v137, v10, v11
	v_cvt_pk_f16_f32 v136, v8, v9
	v_cvt_pk_f16_f32 v135, v14, v15
	v_cvt_pk_f16_f32 v134, v12, v13
	v_lshl_add_u64 v[138:139], v[138:139], 0, v[158:159]
	global_store_dwordx4 v[138:139], v[134:137], off
	s_waitcnt vmcnt(7)
	v_cvt_f32_f16_e32 v140, v130
	v_cvt_f32_f16_sdwa v141, v130 dst_sel:DWORD dst_unused:UNUSED_PAD src0_sel:WORD_1
	v_cvt_f32_f16_e32 v134, v133
	v_cvt_f32_f16_sdwa v135, v133 dst_sel:DWORD dst_unused:UNUSED_PAD src0_sel:WORD_1
	v_cvt_f32_f16_e32 v136, v132
	v_cvt_f32_f16_sdwa v137, v132 dst_sel:DWORD dst_unused:UNUSED_PAD src0_sel:WORD_1
	v_cvt_f32_f16_e32 v132, v131
	v_cvt_f32_f16_sdwa v133, v131 dst_sel:DWORD dst_unused:UNUSED_PAD src0_sel:WORD_1
	v_pk_add_f32 v[4:5], v[4:5], v[140:141]
	v_pk_add_f32 v[0:1], v[0:1], v[136:137]
	v_pk_add_f32 v[2:3], v[2:3], v[134:135]
	v_pk_add_f32 v[6:7], v[6:7], v[132:133]
	v_cvt_pk_f16_f32 v133, v2, v3
	v_cvt_pk_f16_f32 v132, v0, v1
	v_cvt_pk_f16_f32 v131, v6, v7
	v_cvt_pk_f16_f32 v130, v4, v5
	global_store_dwordx4 v[138:139], v[130:133], off offset:256
	v_mul_f32_e32 v134, v117, v117
	v_fmac_f32_e32 v134, v116, v116
	v_and_b32_e32 v131, 64, v236
	v_xor_b32_e32 v130, 16, v236
	v_add_u32_e32 v131, 64, v131
	v_cmp_lt_i32_e32 vcc, v130, v131
	v_xor_b32_e32 v132, 32, v236
	v_mul_f32_e32 v133, v121, v121
	v_cndmask_b32_e32 v130, v236, v130, vcc
	v_cmp_lt_i32_e32 vcc, v132, v131
	v_fmac_f32_e32 v133, v120, v120
	v_lshlrev_b32_e32 v130, 2, v130
	v_cndmask_b32_e32 v131, v236, v132, vcc
	v_mul_f32_e32 v132, v119, v119
	v_fmac_f32_e32 v132, v118, v118
	v_add_f32_e32 v132, v132, v133
	v_mul_f32_e32 v133, v115, v115
	v_fmac_f32_e32 v133, v114, v114
	v_add_f32_e32 v133, v133, v134
	v_add_f32_e32 v132, v132, v133
	v_mul_f32_e32 v133, v127, v127
	v_mul_f32_e32 v134, v129, v129
	v_fmac_f32_e32 v133, v126, v126
	v_fmac_f32_e32 v134, v128, v128
	v_add_f32_e32 v133, v133, v134
	v_add_f32_e32 v132, v133, v132
	v_mul_f32_e32 v133, v123, v123
	v_mul_f32_e32 v134, v125, v125
	v_fmac_f32_e32 v133, v122, v122
	v_fmac_f32_e32 v134, v124, v124
	v_add_f32_e32 v133, v133, v134
	v_add_f32_e32 v132, v133, v132
	ds_bpermute_b32 v133, v130, v132
	v_lshlrev_b32_e32 v131, 2, v131
	s_lshl_b32 s4, s36, 2
	s_waitcnt lgkmcnt(0)
	v_add_f32_e32 v132, v132, v133
	ds_bpermute_b32 v133, v131, v132
	v_cmp_gt_u32_e32 vcc, 16, v32
	s_add_i32 s10, s4, 0
	s_and_saveexec_b64 s[4:5], vcc
	s_cbranch_execz .LBB0_1179
	s_lshl_b32 s11, s20, 10
	s_add_i32 s11, s10, s11
	v_lshl_add_u32 v134, v174, 4, s11
	s_waitcnt lgkmcnt(0)
	v_add_f32_e32 v132, v132, v133
	ds_write_b32 v134, v132

; __device__ __forceinline__ float bf_lo(unsigned w) { return __uint_as_float(w << 16); }
; #define PG8_BAR __builtin_amdgcn_s_barrier()
;     __device__ __forceinline__ void fused(f32x4 (&acc)[2][2][4][2], const Unit& u, int wr, int wc, int fr, int fq, PG8_LAS unsigned char* lds, int wid, int lane) const {
;     ...
;         for (int ai = 0; ai < 2; ++ai) {
;             h16x8 hraw[4][2]; u32x4 eraw[4][2];
; #pragma unroll
;             for (int m = 0; m < 4; ++m) { const size_t off = (size_t)(u.pm * BM + ai * HALF + wr * 64 + m * 16 + fr) * ld + col0;
; #pragma unroll
;                 for (int bj = 0; bj < 2; ++bj) { hraw[m][bj] = *(const h16x8*)(H + off + bj * HALF); if (MODE != 0) eraw[m][bj] = *(const u32x4*)(E + off + bj * HALF); } }
; #pragma unroll
;             for (int m = 0; m < 4; ++m) { const size_t off = (size_t)(u.pm * BM + ai * HALF + wr * 64 + m * 16 + fr) * ld + col0;
; #pragma unroll
;                 for (int bj = 0; bj < 2; ++bj) { const f32x8 hv = __builtin_convertvector(hraw[m][bj], f32x8); f32x8 r8;
; #pragma unroll
;                     for (int n = 0; n < 2; ++n) { f32x4 r; const f32x4 a = acc[ai][bj][m][n];
;                         if (MODE == 0) { r[0] = hv[4 * n] + a[0]; r[1] = hv[4 * n + 1] + a[1]; r[2] = hv[4 * n + 2] + a[2]; r[3] = hv[4 * n + 3] + a[3]; }
;                         else { const unsigned e0 = n ? eraw[m][bj].z : eraw[m][bj].x, e1 = n ? eraw[m][bj].w : eraw[m][bj].y;
;                             r[0] = hv[4 * n] + sigmoidf_fast(a[0]) * bf_lo(e0); r[1] = hv[4 * n + 1] + sigmoidf_fast(a[1]) * bf_hi(e0); r[2] = hv[4 * n + 2] + sigmoidf_fast(a[2]) * bf_lo(e1); r[3] = hv[4 * n + 3] + sigmoidf_fast(a[3]) * bf_hi(e1); }
;                         acc[ai][bj][m][n] = r; r8[4 * n] = r[0]; r8[4 * n + 1] = r[1]; r8[4 * n + 2] = r[2]; r8[4 * n + 3] = r[3]; }
;                     *(h16x8*)(H + off + bj * HALF) = __builtin_convertvector(r8, h16x8); }
;                 asm volatile("" : "+v"(acc[ai][0][m][0]), "+v"(acc[ai][0][m][1]), "+v"(acc[ai][1][m][0]), "+v"(acc[ai][1][m][1])); }
; template <class Epi, class Sched, bool ALIGN_EPI = false, bool SP2 = false, bool KHOOK = false>
; __device__ __forceinline__ void gemm_phase(PG8_LAS unsigned char* lds, const Gemm g, const Sched& S, const Epi& E, const int tid_in) {
;     ...
;     PG8_WAIT_V(0);
;     if constexpr (!ALIGN_EPI) { if (wr == 0) PG8_BAR; }
;     PG8_BAR;
.LBB0_1292:
	s_lshl_b64 s[4:5], s[96:97], 25
	v_readlane_b32 s8, v252, 59
	s_add_u32 s4, s8, s4
	v_readlane_b32 s8, v252, 60
	s_addc_u32 s5, s8, s5
	s_lshl_b32 s8, s2, 5
	s_lshl_b32 s9, s0, 8
	v_lshrrev_b32_e32 v130, 1, v215
	s_or_b32 s8, s9, s8
	s_lshl_b32 s16, s20, 8
	v_and_or_b32 v190, v130, 24, s8
	s_add_i32 s8, s16, s41
	v_or_b32_e32 v192, s8, v216
	v_ashrrev_i32_e32 v193, 31, v192
	v_ashrrev_i32_e32 v191, 31, v190
	v_lshlrev_b64 v[130:131], 11, v[192:193]
	v_lshl_add_u64 v[130:131], v[130:131], 0, v[190:191]
	v_readlane_b32 s8, v252, 57
	v_lshlrev_b64 v[130:131], 1, v[130:131]
	v_readlane_b32 s9, v252, 58
	v_or_b32_e32 v206, 16, v192
	v_lshl_add_u64 v[132:133], s[8:9], 0, v[130:131]
	v_lshl_add_u64 v[130:131], s[4:5], 0, v[130:131]
	global_load_dwordx4 v[198:201], v[132:133], off
	global_load_dwordx4 v[186:189], v[130:131], off
	global_load_dwordx4 v[182:185], v[132:133], off offset:256
	global_load_dwordx4 v[178:181], v[130:131], off offset:256
	v_ashrrev_i32_e32 v207, 31, v206
	v_lshlrev_b64 v[130:131], 11, v[206:207]
	v_lshl_add_u64 v[130:131], v[130:131], 0, v[190:191]
	v_lshlrev_b64 v[130:131], 1, v[130:131]
	v_lshl_add_u64 v[132:133], s[8:9], 0, v[130:131]
	v_lshl_add_u64 v[130:131], s[4:5], 0, v[130:131]
	global_load_dwordx4 v[174:177], v[132:133], off
	global_load_dwordx4 v[170:173], v[130:131], off
	global_load_dwordx4 v[166:169], v[132:133], off offset:256
	global_load_dwordx4 v[162:165], v[130:131], off offset:256
	v_or_b32_e32 v204, 32, v192
	v_ashrrev_i32_e32 v205, 31, v204
	v_lshlrev_b64 v[130:131], 11, v[204:205]
	v_lshl_add_u64 v[130:131], v[130:131], 0, v[190:191]
	v_lshlrev_b64 v[130:131], 1, v[130:131]
	v_lshl_add_u64 v[132:133], s[8:9], 0, v[130:131]
	v_lshl_add_u64 v[130:131], s[4:5], 0, v[130:131]
	global_load_dwordx4 v[158:161], v[132:133], off
	global_load_dwordx4 v[154:157], v[130:131], off
	global_load_dwordx4 v[150:153], v[132:133], off offset:256
	global_load_dwordx4 v[146:149], v[130:131], off offset:256
	v_or_b32_e32 v202, 48, v192
	v_ashrrev_i32_e32 v203, 31, v202
	v_lshlrev_b64 v[130:131], 11, v[202:203]
	v_lshl_add_u64 v[130:131], v[130:131], 0, v[190:191]
	v_lshlrev_b64 v[130:131], 1, v[130:131]
	v_lshl_add_u64 v[132:133], s[8:9], 0, v[130:131]
	v_lshl_add_u64 v[130:131], s[4:5], 0, v[130:131]
	global_load_dwordx4 v[142:145], v[132:133], off
	global_load_dwordx4 v[138:141], v[130:131], off
	global_load_dwordx4 v[134:137], v[132:133], off offset:256
	s_nop 0
	global_load_dwordx4 v[130:133], v[130:131], off offset:256
	s_waitcnt vmcnt(0)
	s_cmpk_gt_u32 s18, 0xff
	s_cbranch_scc1 .LBB0_1294
	s_barrier
.LBB0_1294:
	s_barrier
	v_mul_f32_e32 v56, 0xbfb8aa3b, v56
	v_mul_f32_e32 v57, 0xbfb8aa3b, v57
	v_exp_f32_e32 v56, v56
	v_exp_f32_e32 v57, v57
	v_mul_f32_e32 v62, 0xbfb8aa3b, v62
	v_mul_f32_e32 v63, 0xbfb8aa3b, v63
	v_exp_f32_e32 v62, v62
	v_exp_f32_e32 v63, v63
	v_mul_f32_e32 v64, 0xbfb8aa3b, v64
	v_mul_f32_e32 v65, 0xbfb8aa3b, v65
	v_mul_f32_e32 v54, 0xbfb8aa3b, v54
	v_mul_f32_e32 v55, 0xbfb8aa3b, v55
	v_exp_f32_e32 v64, v64
	v_exp_f32_e32 v65, v65
	v_exp_f32_e32 v54, v54
	v_exp_f32_e32 v55, v55
	v_add_f32_e32 v56, 1.0, v56
	v_add_f32_e32 v57, 1.0, v57
	v_rcp_f32_e32 v56, v56
	v_rcp_f32_e32 v57, v57
	v_add_f32_e32 v62, 1.0, v62
	v_add_f32_e32 v63, 1.0, v63
	v_rcp_f32_e32 v62, v62
	v_rcp_f32_e32 v63, v63
	v_add_f32_e32 v64, 1.0, v64
	v_add_f32_e32 v65, 1.0, v65
	v_add_f32_e32 v54, 1.0, v54
	v_add_f32_e32 v55, 1.0, v55
	v_rcp_f32_e32 v64, v64
	v_rcp_f32_e32 v65, v65
	v_rcp_f32_e32 v54, v54
	v_rcp_f32_e32 v55, v55
	v_mul_f32_e32 v72, 0xbfb8aa3b, v72
	v_mul_f32_e32 v73, 0xbfb8aa3b, v73
	v_exp_f32_e32 v72, v72
	v_exp_f32_e32 v73, v73
	v_mul_f32_e32 v78, 0xbfb8aa3b, v78
	v_mul_f32_e32 v79, 0xbfb8aa3b, v79
	v_mul_f32_e32 v70, 0xbfb8aa3b, v70
	v_mul_f32_e32 v71, 0xbfb8aa3b, v71
	v_exp_f32_e32 v78, v78
	v_exp_f32_e32 v79, v79
	v_mul_f32_e32 v80, 0xbfb8aa3b, v80
	v_mul_f32_e32 v81, 0xbfb8aa3b, v81
	v_exp_f32_e32 v70, v70
	v_exp_f32_e32 v71, v71
	v_exp_f32_e32 v80, v80
	v_exp_f32_e32 v81, v81
	v_add_f32_e32 v72, 1.0, v72
	v_add_f32_e32 v73, 1.0, v73
	v_rcp_f32_e32 v72, v72
	v_rcp_f32_e32 v73, v73
	v_add_f32_e32 v78, 1.0, v78
	s_waitcnt vmcnt(0)
	v_cvt_f32_f16_e32 v212, v199
	v_cvt_f32_f16_sdwa v213, v199 dst_sel:DWORD dst_unused:UNUSED_PAD src0_sel:WORD_1
	v_cvt_f32_f16_e32 v210, v200
	v_cvt_f32_f16_sdwa v211, v200 dst_sel:DWORD dst_unused:UNUSED_PAD src0_sel:WORD_1
	v_cvt_f32_f16_e32 v208, v201
	v_cvt_f32_f16_sdwa v209, v201 dst_sel:DWORD dst_unused:UNUSED_PAD src0_sel:WORD_1
	v_cvt_f32_f16_e32 v200, v198
	v_cvt_f32_f16_sdwa v201, v198 dst_sel:DWORD dst_unused:UNUSED_PAD src0_sel:WORD_1
	v_lshlrev_b32_e32 v198, 16, v186
	v_and_b32_e32 v199, 0xffff0000, v186
	v_lshlrev_b32_e32 v186, 16, v187
	v_and_b32_e32 v187, 0xffff0000, v187
	v_pk_fma_f32 v[56:57], v[56:57], v[186:187], v[212:213]
	v_lshlrev_b32_e32 v186, 16, v188
	v_and_b32_e32 v187, 0xffff0000, v188
	v_pk_fma_f32 v[62:63], v[62:63], v[186:187], v[210:211]
	v_lshlrev_b32_e32 v186, 16, v189
	v_and_b32_e32 v187, 0xffff0000, v189
	v_pk_fma_f32 v[64:65], v[64:65], v[186:187], v[208:209]
	v_lshlrev_b64 v[186:187], 12, v[192:193]
	v_pk_fma_f32 v[54:55], v[54:55], v[198:199], v[200:201]
	v_lshl_add_u64 v[188:189], s[8:9], 0, v[186:187]
	v_lshlrev_b64 v[186:187], 1, v[190:191]
	v_cvt_pk_f16_f32 v201, v64, v65
	v_cvt_pk_f16_f32 v200, v62, v63
	v_cvt_pk_f16_f32 v199, v56, v57
	v_cvt_pk_f16_f32 v198, v54, v55
	v_lshl_add_u64 v[188:189], v[188:189], 0, v[186:187]
	global_store_dwordx4 v[188:189], v[198:201], off
	v_add_f32_e32 v79, 1.0, v79
	v_add_f32_e32 v70, 1.0, v70
	v_cvt_f32_f16_e32 v198, v185
	v_cvt_f32_f16_sdwa v199, v185 dst_sel:DWORD dst_unused:UNUSED_PAD src0_sel:WORD_1
; __device__ __forceinline__ float bf_lo(unsigned w) { return __uint_as_float(w << 16); }
; __device__ __forceinline__ float bf_hi(unsigned w) { return __uint_as_float(w & 0xffff0000u); }
; __device__ __forceinline__ float sigmoidf_fast(float x) { return __builtin_amdgcn_rcpf(1.0f + __expf(-x)); }
;     __device__ __forceinline__ void fused(f32x4 (&acc)[2][2][4][2], const Unit& u, int wr, int wc, int fr, int fq, PG8_LAS unsigned char* lds, int wid, int lane) const {
;     ...
;             for (int m = 0; m < 4; ++m) { const size_t off = (size_t)(u.pm * BM + ai * HALF + wr * 64 + m * 16 + fr) * ld + col0;
; #pragma unroll
;                 for (int bj = 0; bj < 2; ++bj) { const f32x8 hv = __builtin_convertvector(hraw[m][bj], f32x8); f32x8 r8;
; #pragma unroll
;                     for (int n = 0; n < 2; ++n) { f32x4 r; const f32x4 a = acc[ai][bj][m][n];
;                         if (MODE == 0) { r[0] = hv[4 * n] + a[0]; r[1] = hv[4 * n + 1] + a[1]; r[2] = hv[4 * n + 2] + a[2]; r[3] = hv[4 * n + 3] + a[3]; }
;                         else { const unsigned e0 = n ? eraw[m][bj].z : eraw[m][bj].x, e1 = n ? eraw[m][bj].w : eraw[m][bj].y;
;                             r[0] = hv[4 * n] + sigmoidf_fast(a[0]) * bf_lo(e0); r[1] = hv[4 * n + 1] + sigmoidf_fast(a[1]) * bf_hi(e0); r[2] = hv[4 * n + 2] + sigmoidf_fast(a[2]) * bf_lo(e1); r[3] = hv[4 * n + 3] + sigmoidf_fast(a[3]) * bf_hi(e1); }
;                         acc[ai][bj][m][n] = r; r8[4 * n] = r[0]; r8[4 * n + 1] = r[1]; r8[4 * n + 2] = r[2]; r8[4 * n + 3] = r[3]; }
;                     *(h16x8*)(H + off + bj * HALF) = __builtin_convertvector(r8, h16x8); }
;                 asm volatile("" : "+v"(acc[ai][0][m][0]), "+v"(acc[ai][0][m][1]), "+v"(acc[ai][1][m][0]), "+v"(acc[ai][1][m][1])); }
	v_cvt_f32_f16_e32 v200, v184
	v_cvt_f32_f16_sdwa v201, v184 dst_sel:DWORD dst_unused:UNUSED_PAD src0_sel:WORD_1
	v_cvt_f32_f16_e32 v184, v183
	v_cvt_f32_f16_sdwa v185, v183 dst_sel:DWORD dst_unused:UNUSED_PAD src0_sel:WORD_1
	v_add_f32_e32 v71, 1.0, v71
	v_rcp_f32_e32 v78, v78
	v_rcp_f32_e32 v79, v79
	v_add_f32_e32 v80, 1.0, v80
	v_add_f32_e32 v81, 1.0, v81
	v_cvt_f32_f16_e32 v208, v182
	v_cvt_f32_f16_sdwa v209, v182 dst_sel:DWORD dst_unused:UNUSED_PAD src0_sel:WORD_1
	v_rcp_f32_e32 v70, v70
	v_rcp_f32_e32 v71, v71
	v_rcp_f32_e32 v80, v80
	v_rcp_f32_e32 v81, v81
	v_mul_f32_e32 v84, 0xbfb8aa3b, v84
	v_mul_f32_e32 v85, 0xbfb8aa3b, v85
	v_lshlrev_b32_e32 v182, 16, v178
	v_and_b32_e32 v183, 0xffff0000, v178
	v_lshlrev_b32_e32 v178, 16, v179
	v_and_b32_e32 v179, 0xffff0000, v179
	v_mul_f32_e32 v82, 0xbfb8aa3b, v82
	v_mul_f32_e32 v83, 0xbfb8aa3b, v83
	v_exp_f32_e32 v84, v84
	v_exp_f32_e32 v85, v85
	v_mul_f32_e32 v86, 0xbfb8aa3b, v86
	v_mul_f32_e32 v87, 0xbfb8aa3b, v87
	v_pk_fma_f32 v[72:73], v[72:73], v[178:179], v[184:185]
	v_lshlrev_b32_e32 v178, 16, v180
	v_and_b32_e32 v179, 0xffff0000, v180
	v_exp_f32_e32 v82, v82
	v_exp_f32_e32 v83, v83
	v_exp_f32_e32 v86, v86
	v_exp_f32_e32 v87, v87
	v_mul_f32_e32 v88, 0xbfb8aa3b, v88
	v_mul_f32_e32 v89, 0xbfb8aa3b, v89
	v_pk_fma_f32 v[78:79], v[78:79], v[178:179], v[200:201]
	v_lshlrev_b32_e32 v178, 16, v181
	v_and_b32_e32 v179, 0xffff0000, v181
	v_exp_f32_e32 v88, v88
	v_exp_f32_e32 v89, v89
	v_pk_fma_f32 v[70:71], v[70:71], v[182:183], v[208:209]
	v_pk_fma_f32 v[80:81], v[80:81], v[178:179], v[198:199]
	v_cvt_pk_f16_f32 v180, v78, v79
	v_cvt_pk_f16_f32 v181, v80, v81
	v_cvt_pk_f16_f32 v179, v72, v73
	v_cvt_pk_f16_f32 v178, v70, v71
	v_add_f32_e32 v84, 1.0, v84
	v_add_f32_e32 v85, 1.0, v85
	global_store_dwordx4 v[188:189], v[178:181], off offset:256
	v_add_f32_e32 v82, 1.0, v82
	v_add_f32_e32 v83, 1.0, v83
	v_cvt_f32_f16_e32 v178, v177
	v_cvt_f32_f16_sdwa v179, v177 dst_sel:DWORD dst_unused:UNUSED_PAD src0_sel:WORD_1
	v_cvt_f32_f16_e32 v180, v176
	v_cvt_f32_f16_sdwa v181, v176 dst_sel:DWORD dst_unused:UNUSED_PAD src0_sel:WORD_1
	v_cvt_f32_f16_e32 v176, v175
	v_cvt_f32_f16_sdwa v177, v175 dst_sel:DWORD dst_unused:UNUSED_PAD src0_sel:WORD_1
	v_rcp_f32_e32 v84, v84
	v_rcp_f32_e32 v85, v85
	v_add_f32_e32 v86, 1.0, v86
	v_add_f32_e32 v87, 1.0, v87
	v_cvt_f32_f16_e32 v182, v174
	v_cvt_f32_f16_sdwa v183, v174 dst_sel:DWORD dst_unused:UNUSED_PAD src0_sel:WORD_1
	v_rcp_f32_e32 v82, v82
	v_rcp_f32_e32 v83, v83
	v_rcp_f32_e32 v86, v86
	v_rcp_f32_e32 v87, v87
	v_add_f32_e32 v88, 1.0, v88
	v_add_f32_e32 v89, 1.0, v89
	v_rcp_f32_e32 v88, v88
	v_rcp_f32_e32 v89, v89
	v_mul_f32_e32 v92, 0xbfb8aa3b, v92
	v_mul_f32_e32 v93, 0xbfb8aa3b, v93
	v_lshlrev_b32_e32 v174, 16, v170
	v_and_b32_e32 v175, 0xffff0000, v170
	v_lshlrev_b32_e32 v170, 16, v171
	v_and_b32_e32 v171, 0xffff0000, v171
	v_exp_f32_e32 v92, v92
	v_exp_f32_e32 v93, v93
	v_mul_f32_e32 v98, 0xbfb8aa3b, v98
	v_mul_f32_e32 v99, 0xbfb8aa3b, v99
	v_pk_fma_f32 v[84:85], v[84:85], v[170:171], v[176:177]
	v_lshlrev_b32_e32 v170, 16, v172
	v_and_b32_e32 v171, 0xffff0000, v172
	v_mul_f32_e32 v90, 0xbfb8aa3b, v90
	v_mul_f32_e32 v91, 0xbfb8aa3b, v91
	v_exp_f32_e32 v98, v98
	v_exp_f32_e32 v99, v99
	v_mul_f32_e32 v100, 0xbfb8aa3b, v100
	v_mul_f32_e32 v101, 0xbfb8aa3b, v101
	v_pk_fma_f32 v[82:83], v[82:83], v[174:175], v[182:183]
	v_pk_fma_f32 v[86:87], v[86:87], v[170:171], v[180:181]
	v_lshlrev_b32_e32 v170, 16, v173
	v_and_b32_e32 v171, 0xffff0000, v173
	v_lshlrev_b64 v[174:175], 12, v[206:207]
	v_exp_f32_e32 v90, v90
	v_exp_f32_e32 v91, v91
	v_exp_f32_e32 v100, v100
	v_exp_f32_e32 v101, v101
	v_pk_fma_f32 v[88:89], v[88:89], v[170:171], v[178:179]
	v_lshl_add_u64 v[174:175], s[8:9], 0, v[174:175]
	v_cvt_pk_f16_f32 v173, v88, v89
	v_cvt_pk_f16_f32 v172, v86, v87
	v_cvt_pk_f16_f32 v171, v84, v85
	v_cvt_pk_f16_f32 v170, v82, v83
	v_lshl_add_u64 v[174:175], v[174:175], 0, v[186:187]
	v_add_f32_e32 v92, 1.0, v92
	v_add_f32_e32 v93, 1.0, v93
	global_store_dwordx4 v[174:175], v[170:173], off
	v_rcp_f32_e32 v92, v92
	v_rcp_f32_e32 v93, v93
	v_cvt_f32_f16_e32 v170, v169
	v_cvt_f32_f16_sdwa v171, v169 dst_sel:DWORD dst_unused:UNUSED_PAD src0_sel:WORD_1
	v_cvt_f32_f16_e32 v172, v168
	v_cvt_f32_f16_sdwa v173, v168 dst_sel:DWORD dst_unused:UNUSED_PAD src0_sel:WORD_1
	v_cvt_f32_f16_e32 v168, v167
	v_cvt_f32_f16_sdwa v169, v167 dst_sel:DWORD dst_unused:UNUSED_PAD src0_sel:WORD_1
	v_add_f32_e32 v98, 1.0, v98
	v_add_f32_e32 v99, 1.0, v99
	v_add_f32_e32 v90, 1.0, v90
	v_add_f32_e32 v91, 1.0, v91
	v_rcp_f32_e32 v98, v98
	v_rcp_f32_e32 v99, v99
	v_add_f32_e32 v100, 1.0, v100
	v_add_f32_e32 v101, 1.0, v101
	v_cvt_f32_f16_e32 v176, v166
	v_cvt_f32_f16_sdwa v177, v166 dst_sel:DWORD dst_unused:UNUSED_PAD src0_sel:WORD_1
	v_rcp_f32_e32 v90, v90
	v_rcp_f32_e32 v91, v91
	v_rcp_f32_e32 v100, v100
	v_rcp_f32_e32 v101, v101
	v_mul_f32_e32 v108, 0xbfb8aa3b, v108
	v_mul_f32_e32 v109, 0xbfb8aa3b, v109
	v_lshlrev_b32_e32 v166, 16, v162
	v_and_b32_e32 v167, 0xffff0000, v162
	v_lshlrev_b32_e32 v162, 16, v163
	v_and_b32_e32 v163, 0xffff0000, v163
	v_mul_f32_e32 v106, 0xbfb8aa3b, v106
	v_mul_f32_e32 v107, 0xbfb8aa3b, v107
	v_exp_f32_e32 v108, v108
	v_exp_f32_e32 v109, v109
	v_mul_f32_e32 v110, 0xbfb8aa3b, v110
	v_mul_f32_e32 v111, 0xbfb8aa3b, v111
	v_pk_fma_f32 v[92:93], v[92:93], v[162:163], v[168:169]
	v_lshlrev_b32_e32 v162, 16, v164
	v_and_b32_e32 v163, 0xffff0000, v164
	v_exp_f32_e32 v106, v106
	v_exp_f32_e32 v107, v107
	v_exp_f32_e32 v110, v110
	v_exp_f32_e32 v111, v111
	v_mul_f32_e32 v112, 0xbfb8aa3b, v112
	v_mul_f32_e32 v113, 0xbfb8aa3b, v113
	v_pk_fma_f32 v[98:99], v[98:99], v[162:163], v[172:173]
; __device__ __forceinline__ float bf_lo(unsigned w) { return __uint_as_float(w << 16); }
; __device__ __forceinline__ float bf_hi(unsigned w) { return __uint_as_float(w & 0xffff0000u); }
; __device__ __forceinline__ float sigmoidf_fast(float x) { return __builtin_amdgcn_rcpf(1.0f + __expf(-x)); }
;     __device__ __forceinline__ void fused(f32x4 (&acc)[2][2][4][2], const Unit& u, int wr, int wc, int fr, int fq, PG8_LAS unsigned char* lds, int wid, int lane) const {
;     ...
;             for (int m = 0; m < 4; ++m) { const size_t off = (size_t)(u.pm * BM + ai * HALF + wr * 64 + m * 16 + fr) * ld + col0;
; #pragma unroll
;                 for (int bj = 0; bj < 2; ++bj) { const f32x8 hv = __builtin_convertvector(hraw[m][bj], f32x8); f32x8 r8;
; #pragma unroll
;                     for (int n = 0; n < 2; ++n) { f32x4 r; const f32x4 a = acc[ai][bj][m][n];
;                         if (MODE == 0) { r[0] = hv[4 * n] + a[0]; r[1] = hv[4 * n + 1] + a[1]; r[2] = hv[4 * n + 2] + a[2]; r[3] = hv[4 * n + 3] + a[3]; }
;                         else { const unsigned e0 = n ? eraw[m][bj].z : eraw[m][bj].x, e1 = n ? eraw[m][bj].w : eraw[m][bj].y;
;                             r[0] = hv[4 * n] + sigmoidf_fast(a[0]) * bf_lo(e0); r[1] = hv[4 * n + 1] + sigmoidf_fast(a[1]) * bf_hi(e0); r[2] = hv[4 * n + 2] + sigmoidf_fast(a[2]) * bf_lo(e1); r[3] = hv[4 * n + 3] + sigmoidf_fast(a[3]) * bf_hi(e1); }
;                         acc[ai][bj][m][n] = r; r8[4 * n] = r[0]; r8[4 * n + 1] = r[1]; r8[4 * n + 2] = r[2]; r8[4 * n + 3] = r[3]; }
;                     *(h16x8*)(H + off + bj * HALF) = __builtin_convertvector(r8, h16x8); }
;                 asm volatile("" : "+v"(acc[ai][0][m][0]), "+v"(acc[ai][0][m][1]), "+v"(acc[ai][1][m][0]), "+v"(acc[ai][1][m][1])); }
	v_lshlrev_b32_e32 v162, 16, v165
	v_and_b32_e32 v163, 0xffff0000, v165
	v_exp_f32_e32 v112, v112
	v_exp_f32_e32 v113, v113
	v_pk_fma_f32 v[90:91], v[90:91], v[166:167], v[176:177]
	v_pk_fma_f32 v[100:101], v[100:101], v[162:163], v[170:171]
	v_cvt_pk_f16_f32 v164, v98, v99
	v_cvt_pk_f16_f32 v165, v100, v101
	v_cvt_pk_f16_f32 v163, v92, v93
	v_cvt_pk_f16_f32 v162, v90, v91
	v_add_f32_e32 v108, 1.0, v108
	v_add_f32_e32 v109, 1.0, v109
	global_store_dwordx4 v[174:175], v[162:165], off offset:256
	v_add_f32_e32 v106, 1.0, v106
	v_add_f32_e32 v107, 1.0, v107
	v_cvt_f32_f16_e32 v162, v161
	v_cvt_f32_f16_sdwa v163, v161 dst_sel:DWORD dst_unused:UNUSED_PAD src0_sel:WORD_1
	v_cvt_f32_f16_e32 v164, v160
	v_cvt_f32_f16_sdwa v165, v160 dst_sel:DWORD dst_unused:UNUSED_PAD src0_sel:WORD_1
	v_cvt_f32_f16_e32 v160, v159
	v_cvt_f32_f16_sdwa v161, v159 dst_sel:DWORD dst_unused:UNUSED_PAD src0_sel:WORD_1
	v_rcp_f32_e32 v108, v108
	v_rcp_f32_e32 v109, v109
	v_add_f32_e32 v110, 1.0, v110
	v_add_f32_e32 v111, 1.0, v111
	v_cvt_f32_f16_e32 v166, v158
	v_cvt_f32_f16_sdwa v167, v158 dst_sel:DWORD dst_unused:UNUSED_PAD src0_sel:WORD_1
	v_rcp_f32_e32 v106, v106
	v_rcp_f32_e32 v107, v107
	v_rcp_f32_e32 v110, v110
	v_rcp_f32_e32 v111, v111
	v_add_f32_e32 v112, 1.0, v112
	v_add_f32_e32 v113, 1.0, v113
	v_rcp_f32_e32 v112, v112
	v_rcp_f32_e32 v113, v113
	v_mul_f32_e32 v116, 0xbfb8aa3b, v116
	v_mul_f32_e32 v117, 0xbfb8aa3b, v117
	v_lshlrev_b32_e32 v158, 16, v154
	v_and_b32_e32 v159, 0xffff0000, v154
	v_lshlrev_b32_e32 v154, 16, v155
	v_and_b32_e32 v155, 0xffff0000, v155
	v_exp_f32_e32 v116, v116
	v_exp_f32_e32 v117, v117
	v_mul_f32_e32 v118, 0xbfb8aa3b, v118
	v_mul_f32_e32 v119, 0xbfb8aa3b, v119
	v_pk_fma_f32 v[108:109], v[108:109], v[154:155], v[160:161]
	v_lshlrev_b32_e32 v154, 16, v156
	v_and_b32_e32 v155, 0xffff0000, v156
	v_mul_f32_e32 v114, 0xbfb8aa3b, v114
	v_mul_f32_e32 v115, 0xbfb8aa3b, v115
	v_exp_f32_e32 v118, v118
	v_exp_f32_e32 v119, v119
	v_mul_f32_e32 v120, 0xbfb8aa3b, v120
	v_mul_f32_e32 v121, 0xbfb8aa3b, v121
	v_pk_fma_f32 v[106:107], v[106:107], v[158:159], v[166:167]
	v_pk_fma_f32 v[110:111], v[110:111], v[154:155], v[164:165]
	v_lshlrev_b32_e32 v154, 16, v157
	v_and_b32_e32 v155, 0xffff0000, v157
	v_lshlrev_b64 v[158:159], 12, v[204:205]
	v_exp_f32_e32 v114, v114
	v_exp_f32_e32 v115, v115
	v_exp_f32_e32 v120, v120
	v_exp_f32_e32 v121, v121
	v_pk_fma_f32 v[112:113], v[112:113], v[154:155], v[162:163]
	v_lshl_add_u64 v[158:159], s[8:9], 0, v[158:159]
	v_cvt_pk_f16_f32 v157, v112, v113
	v_cvt_pk_f16_f32 v156, v110, v111
	v_cvt_pk_f16_f32 v155, v108, v109
	v_cvt_pk_f16_f32 v154, v106, v107
	v_lshl_add_u64 v[158:159], v[158:159], 0, v[186:187]
	v_add_f32_e32 v116, 1.0, v116
	v_add_f32_e32 v117, 1.0, v117
	global_store_dwordx4 v[158:159], v[154:157], off
	v_rcp_f32_e32 v116, v116
	v_rcp_f32_e32 v117, v117
	v_cvt_f32_f16_e32 v154, v153
	v_cvt_f32_f16_sdwa v155, v153 dst_sel:DWORD dst_unused:UNUSED_PAD src0_sel:WORD_1
	v_cvt_f32_f16_e32 v156, v152
	v_cvt_f32_f16_sdwa v157, v152 dst_sel:DWORD dst_unused:UNUSED_PAD src0_sel:WORD_1
	v_cvt_f32_f16_e32 v152, v151
	v_cvt_f32_f16_sdwa v153, v151 dst_sel:DWORD dst_unused:UNUSED_PAD src0_sel:WORD_1
	v_add_f32_e32 v118, 1.0, v118
	v_add_f32_e32 v119, 1.0, v119
	v_add_f32_e32 v114, 1.0, v114
	v_add_f32_e32 v115, 1.0, v115
	v_rcp_f32_e32 v118, v118
	v_rcp_f32_e32 v119, v119
	v_add_f32_e32 v120, 1.0, v120
	v_add_f32_e32 v121, 1.0, v121
	v_cvt_f32_f16_e32 v160, v150
	v_cvt_f32_f16_sdwa v161, v150 dst_sel:DWORD dst_unused:UNUSED_PAD src0_sel:WORD_1
	v_rcp_f32_e32 v114, v114
	v_rcp_f32_e32 v115, v115
	v_rcp_f32_e32 v120, v120
	v_rcp_f32_e32 v121, v121
	v_mul_f32_e32 v128, 0xbfb8aa3b, v128
	v_mul_f32_e32 v129, 0xbfb8aa3b, v129
	v_lshlrev_b32_e32 v150, 16, v146
	v_and_b32_e32 v151, 0xffff0000, v146
	v_lshlrev_b32_e32 v146, 16, v147
	v_and_b32_e32 v147, 0xffff0000, v147
	v_mul_f32_e32 v126, 0xbfb8aa3b, v126
	v_mul_f32_e32 v127, 0xbfb8aa3b, v127
	v_exp_f32_e32 v128, v128
	v_exp_f32_e32 v129, v129
	v_mul_f32_e32 v122, 0xbfb8aa3b, v122
	v_mul_f32_e32 v123, 0xbfb8aa3b, v123
	v_pk_fma_f32 v[116:117], v[116:117], v[146:147], v[152:153]
	v_lshlrev_b32_e32 v146, 16, v148
	v_and_b32_e32 v147, 0xffff0000, v148
	v_exp_f32_e32 v126, v126
	v_exp_f32_e32 v127, v127
	v_exp_f32_e32 v122, v122
	v_exp_f32_e32 v123, v123
	v_mul_f32_e32 v124, 0xbfb8aa3b, v124
	v_mul_f32_e32 v125, 0xbfb8aa3b, v125
	v_pk_fma_f32 v[118:119], v[118:119], v[146:147], v[156:157]
	v_lshlrev_b32_e32 v146, 16, v149
	v_and_b32_e32 v147, 0xffff0000, v149
	v_exp_f32_e32 v124, v124
	v_exp_f32_e32 v125, v125
	v_pk_fma_f32 v[114:115], v[114:115], v[150:151], v[160:161]
	v_pk_fma_f32 v[120:121], v[120:121], v[146:147], v[154:155]
	v_cvt_pk_f16_f32 v148, v118, v119
	v_cvt_pk_f16_f32 v149, v120, v121
	v_cvt_pk_f16_f32 v147, v116, v117
	v_cvt_pk_f16_f32 v146, v114, v115
	v_add_f32_e32 v128, 1.0, v128
	v_add_f32_e32 v129, 1.0, v129
	global_store_dwordx4 v[158:159], v[146:149], off offset:256
	v_add_f32_e32 v126, 1.0, v126
	v_add_f32_e32 v127, 1.0, v127
	v_cvt_f32_f16_e32 v146, v145
	v_cvt_f32_f16_sdwa v147, v145 dst_sel:DWORD dst_unused:UNUSED_PAD src0_sel:WORD_1
	v_cvt_f32_f16_e32 v148, v144
	v_cvt_f32_f16_sdwa v149, v144 dst_sel:DWORD dst_unused:UNUSED_PAD src0_sel:WORD_1
	v_cvt_f32_f16_e32 v144, v143
	v_cvt_f32_f16_sdwa v145, v143 dst_sel:DWORD dst_unused:UNUSED_PAD src0_sel:WORD_1
	v_rcp_f32_e32 v128, v128
	v_rcp_f32_e32 v129, v129
	v_add_f32_e32 v122, 1.0, v122
	v_add_f32_e32 v123, 1.0, v123
	v_cvt_f32_f16_e32 v150, v142
	v_cvt_f32_f16_sdwa v151, v142 dst_sel:DWORD dst_unused:UNUSED_PAD src0_sel:WORD_1
	v_rcp_f32_e32 v126, v126
	v_rcp_f32_e32 v127, v127
	v_rcp_f32_e32 v122, v122
; __device__ __forceinline__ float bf_lo(unsigned w) { return __uint_as_float(w << 16); }
; __device__ __forceinline__ float bf_hi(unsigned w) { return __uint_as_float(w & 0xffff0000u); }
; __device__ __forceinline__ float sigmoidf_fast(float x) { return __builtin_amdgcn_rcpf(1.0f + __expf(-x)); }
;     __device__ __forceinline__ void fused(f32x4 (&acc)[2][2][4][2], const Unit& u, int wr, int wc, int fr, int fq, PG8_LAS unsigned char* lds, int wid, int lane) const {
;     ...
;             for (int m = 0; m < 4; ++m) { const size_t off = (size_t)(u.pm * BM + ai * HALF + wr * 64 + m * 16 + fr) * ld + col0;
; #pragma unroll
;                 for (int bj = 0; bj < 2; ++bj) { hraw[m][bj] = *(const h16x8*)(H + off + bj * HALF); if (MODE != 0) eraw[m][bj] = *(const u32x4*)(E + off + bj * HALF); } }
; #pragma unroll
;             for (int m = 0; m < 4; ++m) { const size_t off = (size_t)(u.pm * BM + ai * HALF + wr * 64 + m * 16 + fr) * ld + col0;
; #pragma unroll
;                 for (int bj = 0; bj < 2; ++bj) { const f32x8 hv = __builtin_convertvector(hraw[m][bj], f32x8); f32x8 r8;
; #pragma unroll
;                     for (int n = 0; n < 2; ++n) { f32x4 r; const f32x4 a = acc[ai][bj][m][n];
;                         if (MODE == 0) { r[0] = hv[4 * n] + a[0]; r[1] = hv[4 * n + 1] + a[1]; r[2] = hv[4 * n + 2] + a[2]; r[3] = hv[4 * n + 3] + a[3]; }
;                         else { const unsigned e0 = n ? eraw[m][bj].z : eraw[m][bj].x, e1 = n ? eraw[m][bj].w : eraw[m][bj].y;
;                             r[0] = hv[4 * n] + sigmoidf_fast(a[0]) * bf_lo(e0); r[1] = hv[4 * n + 1] + sigmoidf_fast(a[1]) * bf_hi(e0); r[2] = hv[4 * n + 2] + sigmoidf_fast(a[2]) * bf_lo(e1); r[3] = hv[4 * n + 3] + sigmoidf_fast(a[3]) * bf_hi(e1); }
;                         acc[ai][bj][m][n] = r; r8[4 * n] = r[0]; r8[4 * n + 1] = r[1]; r8[4 * n + 2] = r[2]; r8[4 * n + 3] = r[3]; }
;                     *(h16x8*)(H + off + bj * HALF) = __builtin_convertvector(r8, h16x8); }
;                 asm volatile("" : "+v"(acc[ai][0][m][0]), "+v"(acc[ai][0][m][1]), "+v"(acc[ai][1][m][0]), "+v"(acc[ai][1][m][1])); }
	v_rcp_f32_e32 v123, v123
	v_add_f32_e32 v124, 1.0, v124
	v_add_f32_e32 v125, 1.0, v125
	v_rcp_f32_e32 v124, v124
	v_rcp_f32_e32 v125, v125
	v_mul_f32_e32 v104, 0xbfb8aa3b, v104
	v_mul_f32_e32 v105, 0xbfb8aa3b, v105
	v_lshlrev_b32_e32 v142, 16, v138
	v_and_b32_e32 v143, 0xffff0000, v138
	v_lshlrev_b32_e32 v138, 16, v139
	v_and_b32_e32 v139, 0xffff0000, v139
	v_exp_f32_e32 v104, v104
	v_exp_f32_e32 v105, v105
	v_mul_f32_e32 v94, 0xbfb8aa3b, v94
	v_mul_f32_e32 v95, 0xbfb8aa3b, v95
	v_pk_fma_f32 v[128:129], v[128:129], v[138:139], v[144:145]
	v_lshlrev_b32_e32 v138, 16, v140
	v_and_b32_e32 v139, 0xffff0000, v140
	v_mul_f32_e32 v102, 0xbfb8aa3b, v102
	v_mul_f32_e32 v103, 0xbfb8aa3b, v103
	v_exp_f32_e32 v94, v94
	v_exp_f32_e32 v95, v95
	v_mul_f32_e32 v96, 0xbfb8aa3b, v96
	v_mul_f32_e32 v97, 0xbfb8aa3b, v97
	v_pk_fma_f32 v[126:127], v[126:127], v[142:143], v[150:151]
	v_pk_fma_f32 v[122:123], v[122:123], v[138:139], v[148:149]
	v_lshlrev_b32_e32 v138, 16, v141
	v_and_b32_e32 v139, 0xffff0000, v141
	v_lshlrev_b64 v[142:143], 12, v[202:203]
	v_exp_f32_e32 v102, v102
	v_exp_f32_e32 v103, v103
	v_exp_f32_e32 v96, v96
	v_exp_f32_e32 v97, v97
	v_pk_fma_f32 v[124:125], v[124:125], v[138:139], v[146:147]
	v_lshl_add_u64 v[142:143], s[8:9], 0, v[142:143]
	v_cvt_pk_f16_f32 v141, v124, v125
	v_cvt_pk_f16_f32 v140, v122, v123
	v_cvt_pk_f16_f32 v139, v128, v129
	v_cvt_pk_f16_f32 v138, v126, v127
	v_lshl_add_u64 v[142:143], v[142:143], 0, v[186:187]
	v_add_f32_e32 v104, 1.0, v104
	v_add_f32_e32 v105, 1.0, v105
	global_store_dwordx4 v[142:143], v[138:141], off
	v_rcp_f32_e32 v104, v104
	v_rcp_f32_e32 v105, v105
	v_cvt_f32_f16_e32 v138, v137
	v_cvt_f32_f16_sdwa v139, v137 dst_sel:DWORD dst_unused:UNUSED_PAD src0_sel:WORD_1
	v_cvt_f32_f16_e32 v140, v136
	v_cvt_f32_f16_sdwa v141, v136 dst_sel:DWORD dst_unused:UNUSED_PAD src0_sel:WORD_1
	v_cvt_f32_f16_e32 v136, v135
	v_cvt_f32_f16_sdwa v137, v135 dst_sel:DWORD dst_unused:UNUSED_PAD src0_sel:WORD_1
	v_add_f32_e32 v94, 1.0, v94
	v_add_f32_e32 v95, 1.0, v95
	v_add_f32_e32 v102, 1.0, v102
	v_add_f32_e32 v103, 1.0, v103
	v_rcp_f32_e32 v94, v94
	v_rcp_f32_e32 v95, v95
	v_add_f32_e32 v96, 1.0, v96
	v_add_f32_e32 v97, 1.0, v97
	v_cvt_f32_f16_e32 v144, v134
	v_cvt_f32_f16_sdwa v145, v134 dst_sel:DWORD dst_unused:UNUSED_PAD src0_sel:WORD_1
	v_rcp_f32_e32 v102, v102
	v_rcp_f32_e32 v103, v103
	v_rcp_f32_e32 v96, v96
	v_rcp_f32_e32 v97, v97
	v_lshlrev_b32_e32 v134, 16, v130
	v_and_b32_e32 v135, 0xffff0000, v130
	v_lshlrev_b32_e32 v130, 16, v131
	v_and_b32_e32 v131, 0xffff0000, v131
	v_pk_fma_f32 v[104:105], v[104:105], v[130:131], v[136:137]
	v_lshlrev_b32_e32 v130, 16, v132
	v_and_b32_e32 v131, 0xffff0000, v132
	v_pk_fma_f32 v[94:95], v[94:95], v[130:131], v[140:141]
	v_lshlrev_b32_e32 v130, 16, v133
	v_and_b32_e32 v131, 0xffff0000, v133
	v_pk_fma_f32 v[102:103], v[102:103], v[134:135], v[144:145]
	v_pk_fma_f32 v[96:97], v[96:97], v[130:131], v[138:139]
	v_add_u32_e32 v206, 0x80, v192
	v_cvt_pk_f16_f32 v133, v96, v97
	v_cvt_pk_f16_f32 v132, v94, v95
	v_cvt_pk_f16_f32 v131, v104, v105
	v_cvt_pk_f16_f32 v130, v102, v103
	v_ashrrev_i32_e32 v207, 31, v206
	global_store_dwordx4 v[142:143], v[130:133], off offset:256
	v_add_u32_e32 v204, 0x90, v192
	v_ashrrev_i32_e32 v205, 31, v204
	v_lshlrev_b64 v[130:131], 11, v[206:207]
	v_lshl_add_u64 v[130:131], v[130:131], 0, v[190:191]
	v_lshlrev_b64 v[130:131], 1, v[130:131]
	v_lshl_add_u64 v[132:133], s[8:9], 0, v[130:131]
	v_lshl_add_u64 v[130:131], s[4:5], 0, v[130:131]
	global_load_dwordx4 v[198:201], v[132:133], off
	global_load_dwordx4 v[208:211], v[130:131], off
	global_load_dwordx4 v[182:185], v[132:133], off offset:256
	global_load_dwordx4 v[178:181], v[130:131], off offset:256
	v_lshlrev_b64 v[130:131], 11, v[204:205]
	v_lshl_add_u64 v[130:131], v[130:131], 0, v[190:191]
	v_lshlrev_b64 v[130:131], 1, v[130:131]
	v_lshl_add_u64 v[132:133], s[8:9], 0, v[130:131]
	v_lshl_add_u64 v[130:131], s[4:5], 0, v[130:131]
	global_load_dwordx4 v[174:177], v[132:133], off
	global_load_dwordx4 v[170:173], v[130:131], off
	global_load_dwordx4 v[166:169], v[132:133], off offset:256
	global_load_dwordx4 v[162:165], v[130:131], off offset:256
	v_add_u32_e32 v202, 0xa0, v192
	v_ashrrev_i32_e32 v203, 31, v202
	v_lshlrev_b64 v[130:131], 11, v[202:203]
	v_lshl_add_u64 v[130:131], v[130:131], 0, v[190:191]
	v_lshlrev_b64 v[130:131], 1, v[130:131]
	v_lshl_add_u64 v[132:133], s[8:9], 0, v[130:131]
	v_lshl_add_u64 v[130:131], s[4:5], 0, v[130:131]
	global_load_dwordx4 v[158:161], v[132:133], off
	global_load_dwordx4 v[154:157], v[130:131], off
	global_load_dwordx4 v[150:153], v[132:133], off offset:256
	global_load_dwordx4 v[146:149], v[130:131], off offset:256
	v_add_u32_e32 v188, 0xb0, v192
	v_ashrrev_i32_e32 v189, 31, v188
	v_lshlrev_b64 v[130:131], 11, v[188:189]
	v_lshl_add_u64 v[130:131], v[130:131], 0, v[190:191]
	v_lshlrev_b64 v[130:131], 1, v[130:131]
	v_lshl_add_u64 v[132:133], s[8:9], 0, v[130:131]
	v_lshl_add_u64 v[130:131], s[4:5], 0, v[130:131]
	global_load_dwordx4 v[142:145], v[132:133], off
	global_load_dwordx4 v[138:141], v[130:131], off
	global_load_dwordx4 v[134:137], v[132:133], off offset:256
	s_nop 0
	global_load_dwordx4 v[130:133], v[130:131], off offset:256
	v_mul_f32_e32 v74, 0xbfb8aa3b, v74
	v_mul_f32_e32 v75, 0xbfb8aa3b, v75
	v_exp_f32_e32 v74, v74
	v_exp_f32_e32 v75, v75
	v_mul_f32_e32 v76, 0xbfb8aa3b, v76
	v_mul_f32_e32 v77, 0xbfb8aa3b, v77
	v_exp_f32_e32 v76, v76
	v_exp_f32_e32 v77, v77
	v_mul_f32_e32 v66, 0xbfb8aa3b, v66
	v_mul_f32_e32 v67, 0xbfb8aa3b, v67
	v_exp_f32_e32 v66, v66
	v_exp_f32_e32 v67, v67
	v_mul_f32_e32 v68, 0xbfb8aa3b, v68
	v_mul_f32_e32 v69, 0xbfb8aa3b, v69
	v_exp_f32_e32 v68, v68
	v_exp_f32_e32 v69, v69
	v_add_f32_e32 v74, 1.0, v74
	v_add_f32_e32 v75, 1.0, v75
	v_rcp_f32_e32 v74, v74
	v_rcp_f32_e32 v75, v75
	v_add_f32_e32 v76, 1.0, v76
	v_add_f32_e32 v77, 1.0, v77
	v_rcp_f32_e32 v76, v76
	v_rcp_f32_e32 v77, v77
	v_add_f32_e32 v66, 1.0, v66
	v_add_f32_e32 v67, 1.0, v67
	v_rcp_f32_e32 v66, v66
	v_rcp_f32_e32 v67, v67
	v_add_f32_e32 v68, 1.0, v68
	v_add_f32_e32 v69, 1.0, v69
	v_rcp_f32_e32 v68, v68
	v_rcp_f32_e32 v69, v69
	v_mul_f32_e32 v60, 0xbfb8aa3b, v60
	v_mul_f32_e32 v61, 0xbfb8aa3b, v61
	v_exp_f32_e32 v60, v60
	v_exp_f32_e32 v61, v61
	v_mul_f32_e32 v50, 0xbfb8aa3b, v50
	v_mul_f32_e32 v51, 0xbfb8aa3b, v51
	v_mul_f32_e32 v58, 0xbfb8aa3b, v58
	v_mul_f32_e32 v59, 0xbfb8aa3b, v59
	v_exp_f32_e32 v50, v50
	v_exp_f32_e32 v51, v51
	v_mul_f32_e32 v52, 0xbfb8aa3b, v52
	v_mul_f32_e32 v53, 0xbfb8aa3b, v53
	v_exp_f32_e32 v58, v58
	v_exp_f32_e32 v59, v59
	v_exp_f32_e32 v52, v52
	v_exp_f32_e32 v53, v53
	v_add_f32_e32 v60, 1.0, v60
	v_add_f32_e32 v61, 1.0, v61
	v_rcp_f32_e32 v60, v60
	v_rcp_f32_e32 v61, v61
	v_add_f32_e32 v50, 1.0, v50
	v_add_f32_e32 v51, 1.0, v51
	s_waitcnt vmcnt(15)
; __device__ __forceinline__ float bf_lo(unsigned w) { return __uint_as_float(w << 16); }
; __device__ __forceinline__ float bf_hi(unsigned w) { return __uint_as_float(w & 0xffff0000u); }
; __device__ __forceinline__ float sigmoidf_fast(float x) { return __builtin_amdgcn_rcpf(1.0f + __expf(-x)); }
;     __device__ __forceinline__ void fused(f32x4 (&acc)[2][2][4][2], const Unit& u, int wr, int wc, int fr, int fq, PG8_LAS unsigned char* lds, int wid, int lane) const {
;     ...
;             for (int m = 0; m < 4; ++m) { const size_t off = (size_t)(u.pm * BM + ai * HALF + wr * 64 + m * 16 + fr) * ld + col0;
; #pragma unroll
;                 for (int bj = 0; bj < 2; ++bj) { const f32x8 hv = __builtin_convertvector(hraw[m][bj], f32x8); f32x8 r8;
; #pragma unroll
;                     for (int n = 0; n < 2; ++n) { f32x4 r; const f32x4 a = acc[ai][bj][m][n];
;                         if (MODE == 0) { r[0] = hv[4 * n] + a[0]; r[1] = hv[4 * n + 1] + a[1]; r[2] = hv[4 * n + 2] + a[2]; r[3] = hv[4 * n + 3] + a[3]; }
;                         else { const unsigned e0 = n ? eraw[m][bj].z : eraw[m][bj].x, e1 = n ? eraw[m][bj].w : eraw[m][bj].y;
;                             r[0] = hv[4 * n] + sigmoidf_fast(a[0]) * bf_lo(e0); r[1] = hv[4 * n + 1] + sigmoidf_fast(a[1]) * bf_hi(e0); r[2] = hv[4 * n + 2] + sigmoidf_fast(a[2]) * bf_lo(e1); r[3] = hv[4 * n + 3] + sigmoidf_fast(a[3]) * bf_hi(e1); }
;                         acc[ai][bj][m][n] = r; r8[4 * n] = r[0]; r8[4 * n + 1] = r[1]; r8[4 * n + 2] = r[2]; r8[4 * n + 3] = r[3]; }
;                     *(h16x8*)(H + off + bj * HALF) = __builtin_convertvector(r8, h16x8); }
;                 asm volatile("" : "+v"(acc[ai][0][m][0]), "+v"(acc[ai][0][m][1]), "+v"(acc[ai][1][m][0]), "+v"(acc[ai][1][m][1])); }
	v_cvt_f32_f16_e32 v218, v198
	v_cvt_f32_f16_sdwa v219, v198 dst_sel:DWORD dst_unused:UNUSED_PAD src0_sel:WORD_1
	v_cvt_f32_f16_e32 v192, v201
	v_cvt_f32_f16_sdwa v193, v201 dst_sel:DWORD dst_unused:UNUSED_PAD src0_sel:WORD_1
	v_cvt_f32_f16_e32 v212, v200
	v_cvt_f32_f16_sdwa v213, v200 dst_sel:DWORD dst_unused:UNUSED_PAD src0_sel:WORD_1
	v_cvt_f32_f16_e32 v200, v199
	v_cvt_f32_f16_sdwa v201, v199 dst_sel:DWORD dst_unused:UNUSED_PAD src0_sel:WORD_1
	s_waitcnt vmcnt(14)
	v_lshlrev_b32_e32 v198, 16, v208
	v_and_b32_e32 v199, 0xffff0000, v208
	v_pk_fma_f32 v[74:75], v[74:75], v[198:199], v[218:219]
	v_lshlrev_b32_e32 v198, 16, v209
	v_and_b32_e32 v199, 0xffff0000, v209
	v_pk_fma_f32 v[76:77], v[76:77], v[198:199], v[200:201]
	v_lshlrev_b32_e32 v198, 16, v210
	v_and_b32_e32 v199, 0xffff0000, v210
	v_pk_fma_f32 v[66:67], v[66:67], v[198:199], v[212:213]
	v_lshlrev_b32_e32 v198, 16, v211
	v_and_b32_e32 v199, 0xffff0000, v211
	v_pk_fma_f32 v[68:69], v[68:69], v[198:199], v[192:193]
	v_lshlrev_b64 v[192:193], 12, v[206:207]
	v_lshl_add_u64 v[192:193], s[8:9], 0, v[192:193]
	v_cvt_pk_f16_f32 v201, v68, v69
	v_cvt_pk_f16_f32 v200, v66, v67
	v_cvt_pk_f16_f32 v199, v76, v77
	v_cvt_pk_f16_f32 v198, v74, v75
	v_lshl_add_u64 v[192:193], v[192:193], 0, v[186:187]
	global_store_dwordx4 v[192:193], v[198:201], off
	v_add_f32_e32 v58, 1.0, v58
	v_add_f32_e32 v59, 1.0, v59
	s_waitcnt vmcnt(14)
	v_cvt_f32_f16_e32 v198, v185
	v_cvt_f32_f16_sdwa v199, v185 dst_sel:DWORD dst_unused:UNUSED_PAD src0_sel:WORD_1
	v_cvt_f32_f16_e32 v200, v184
	v_cvt_f32_f16_sdwa v201, v184 dst_sel:DWORD dst_unused:UNUSED_PAD src0_sel:WORD_1
	v_cvt_f32_f16_e32 v184, v183
	v_cvt_f32_f16_sdwa v185, v183 dst_sel:DWORD dst_unused:UNUSED_PAD src0_sel:WORD_1
	v_rcp_f32_e32 v50, v50
	v_rcp_f32_e32 v51, v51
	v_add_f32_e32 v52, 1.0, v52
	v_add_f32_e32 v53, 1.0, v53
	v_cvt_f32_f16_e32 v206, v182
	v_cvt_f32_f16_sdwa v207, v182 dst_sel:DWORD dst_unused:UNUSED_PAD src0_sel:WORD_1
	v_rcp_f32_e32 v58, v58
	v_rcp_f32_e32 v59, v59
	v_rcp_f32_e32 v52, v52
	v_rcp_f32_e32 v53, v53
	v_mul_f32_e32 v48, 0xbfb8aa3b, v48
	v_mul_f32_e32 v49, 0xbfb8aa3b, v49
	s_waitcnt vmcnt(13)
	v_lshlrev_b32_e32 v182, 16, v178
	v_and_b32_e32 v183, 0xffff0000, v178
	v_lshlrev_b32_e32 v178, 16, v179
	v_and_b32_e32 v179, 0xffff0000, v179
	v_mul_f32_e32 v46, 0xbfb8aa3b, v46
	v_mul_f32_e32 v47, 0xbfb8aa3b, v47
	v_exp_f32_e32 v48, v48
	v_exp_f32_e32 v49, v49
	v_mul_f32_e32 v42, 0xbfb8aa3b, v42
	v_mul_f32_e32 v43, 0xbfb8aa3b, v43
	v_pk_fma_f32 v[60:61], v[60:61], v[178:179], v[184:185]
	v_lshlrev_b32_e32 v178, 16, v180
	v_and_b32_e32 v179, 0xffff0000, v180
	v_exp_f32_e32 v46, v46
	v_exp_f32_e32 v47, v47
	v_exp_f32_e32 v42, v42
	v_exp_f32_e32 v43, v43
	v_mul_f32_e32 v44, 0xbfb8aa3b, v44
	v_mul_f32_e32 v45, 0xbfb8aa3b, v45
	v_pk_fma_f32 v[50:51], v[50:51], v[178:179], v[200:201]
	v_lshlrev_b32_e32 v178, 16, v181
	v_and_b32_e32 v179, 0xffff0000, v181
	v_exp_f32_e32 v44, v44
	v_exp_f32_e32 v45, v45
	v_pk_fma_f32 v[58:59], v[58:59], v[182:183], v[206:207]
	v_pk_fma_f32 v[52:53], v[52:53], v[178:179], v[198:199]
	v_cvt_pk_f16_f32 v180, v50, v51
	v_cvt_pk_f16_f32 v181, v52, v53
	v_cvt_pk_f16_f32 v179, v60, v61
	v_cvt_pk_f16_f32 v178, v58, v59
	v_add_f32_e32 v48, 1.0, v48
	v_add_f32_e32 v49, 1.0, v49
	global_store_dwordx4 v[192:193], v[178:181], off offset:256
	v_add_f32_e32 v46, 1.0, v46
	v_add_f32_e32 v47, 1.0, v47
	s_waitcnt vmcnt(13)
	v_cvt_f32_f16_e32 v178, v177
	v_cvt_f32_f16_sdwa v179, v177 dst_sel:DWORD dst_unused:UNUSED_PAD src0_sel:WORD_1
	v_cvt_f32_f16_e32 v180, v176
	v_cvt_f32_f16_sdwa v181, v176 dst_sel:DWORD dst_unused:UNUSED_PAD src0_sel:WORD_1
	v_cvt_f32_f16_e32 v176, v175
	v_cvt_f32_f16_sdwa v177, v175 dst_sel:DWORD dst_unused:UNUSED_PAD src0_sel:WORD_1
	v_rcp_f32_e32 v48, v48
	v_rcp_f32_e32 v49, v49
	v_add_f32_e32 v42, 1.0, v42
	v_add_f32_e32 v43, 1.0, v43
	v_cvt_f32_f16_e32 v182, v174
	v_cvt_f32_f16_sdwa v183, v174 dst_sel:DWORD dst_unused:UNUSED_PAD src0_sel:WORD_1
	v_rcp_f32_e32 v46, v46
	v_rcp_f32_e32 v47, v47
	v_rcp_f32_e32 v42, v42
	v_rcp_f32_e32 v43, v43
	v_add_f32_e32 v44, 1.0, v44
	v_add_f32_e32 v45, 1.0, v45
	v_rcp_f32_e32 v44, v44
	v_rcp_f32_e32 v45, v45
	v_mul_f32_e32 v40, 0xbfb8aa3b, v40
	v_mul_f32_e32 v41, 0xbfb8aa3b, v41
	s_waitcnt vmcnt(12)
	v_lshlrev_b32_e32 v174, 16, v170
	v_and_b32_e32 v175, 0xffff0000, v170
	v_lshlrev_b32_e32 v170, 16, v171
	v_and_b32_e32 v171, 0xffff0000, v171
	v_exp_f32_e32 v40, v40
	v_exp_f32_e32 v41, v41
	v_mul_f32_e32 v34, 0xbfb8aa3b, v34
	v_mul_f32_e32 v35, 0xbfb8aa3b, v35
	v_pk_fma_f32 v[48:49], v[48:49], v[170:171], v[176:177]
	v_lshlrev_b32_e32 v170, 16, v172
	v_and_b32_e32 v171, 0xffff0000, v172
	v_mul_f32_e32 v38, 0xbfb8aa3b, v38
	v_mul_f32_e32 v39, 0xbfb8aa3b, v39
	v_exp_f32_e32 v34, v34
	v_exp_f32_e32 v35, v35
	v_mul_f32_e32 v36, 0xbfb8aa3b, v36
	v_mul_f32_e32 v37, 0xbfb8aa3b, v37
	v_pk_fma_f32 v[46:47], v[46:47], v[174:175], v[182:183]
	v_pk_fma_f32 v[42:43], v[42:43], v[170:171], v[180:181]
	v_lshlrev_b32_e32 v170, 16, v173
	v_and_b32_e32 v171, 0xffff0000, v173
	v_lshlrev_b64 v[174:175], 12, v[204:205]
	v_exp_f32_e32 v38, v38
	v_exp_f32_e32 v39, v39
	v_exp_f32_e32 v36, v36
	v_exp_f32_e32 v37, v37
	v_pk_fma_f32 v[44:45], v[44:45], v[170:171], v[178:179]
	v_lshl_add_u64 v[174:175], s[8:9], 0, v[174:175]
	v_cvt_pk_f16_f32 v173, v44, v45
	v_cvt_pk_f16_f32 v172, v42, v43
	v_cvt_pk_f16_f32 v171, v48, v49
	v_cvt_pk_f16_f32 v170, v46, v47
	v_lshl_add_u64 v[174:175], v[174:175], 0, v[186:187]
	v_add_f32_e32 v40, 1.0, v40
	v_add_f32_e32 v41, 1.0, v41
	global_store_dwordx4 v[174:175], v[170:173], off
	v_rcp_f32_e32 v40, v40
	v_rcp_f32_e32 v41, v41
	s_waitcnt vmcnt(12)
; __device__ __forceinline__ float bf_lo(unsigned w) { return __uint_as_float(w << 16); }
; __device__ __forceinline__ float bf_hi(unsigned w) { return __uint_as_float(w & 0xffff0000u); }
; __device__ __forceinline__ float sigmoidf_fast(float x) { return __builtin_amdgcn_rcpf(1.0f + __expf(-x)); }
;     __device__ __forceinline__ void fused(f32x4 (&acc)[2][2][4][2], const Unit& u, int wr, int wc, int fr, int fq, PG8_LAS unsigned char* lds, int wid, int lane) const {
;     ...
;             for (int m = 0; m < 4; ++m) { const size_t off = (size_t)(u.pm * BM + ai * HALF + wr * 64 + m * 16 + fr) * ld + col0;
; #pragma unroll
;                 for (int bj = 0; bj < 2; ++bj) { const f32x8 hv = __builtin_convertvector(hraw[m][bj], f32x8); f32x8 r8;
; #pragma unroll
;                     for (int n = 0; n < 2; ++n) { f32x4 r; const f32x4 a = acc[ai][bj][m][n];
;                         if (MODE == 0) { r[0] = hv[4 * n] + a[0]; r[1] = hv[4 * n + 1] + a[1]; r[2] = hv[4 * n + 2] + a[2]; r[3] = hv[4 * n + 3] + a[3]; }
;                         else { const unsigned e0 = n ? eraw[m][bj].z : eraw[m][bj].x, e1 = n ? eraw[m][bj].w : eraw[m][bj].y;
;                             r[0] = hv[4 * n] + sigmoidf_fast(a[0]) * bf_lo(e0); r[1] = hv[4 * n + 1] + sigmoidf_fast(a[1]) * bf_hi(e0); r[2] = hv[4 * n + 2] + sigmoidf_fast(a[2]) * bf_lo(e1); r[3] = hv[4 * n + 3] + sigmoidf_fast(a[3]) * bf_hi(e1); }
;                         acc[ai][bj][m][n] = r; r8[4 * n] = r[0]; r8[4 * n + 1] = r[1]; r8[4 * n + 2] = r[2]; r8[4 * n + 3] = r[3]; }
;                     *(h16x8*)(H + off + bj * HALF) = __builtin_convertvector(r8, h16x8); }
;                 asm volatile("" : "+v"(acc[ai][0][m][0]), "+v"(acc[ai][0][m][1]), "+v"(acc[ai][1][m][0]), "+v"(acc[ai][1][m][1])); }
	v_cvt_f32_f16_e32 v170, v169
	v_cvt_f32_f16_sdwa v171, v169 dst_sel:DWORD dst_unused:UNUSED_PAD src0_sel:WORD_1
	v_cvt_f32_f16_e32 v172, v168
	v_cvt_f32_f16_sdwa v173, v168 dst_sel:DWORD dst_unused:UNUSED_PAD src0_sel:WORD_1
	v_cvt_f32_f16_e32 v168, v167
	v_cvt_f32_f16_sdwa v169, v167 dst_sel:DWORD dst_unused:UNUSED_PAD src0_sel:WORD_1
	v_add_f32_e32 v34, 1.0, v34
	v_add_f32_e32 v35, 1.0, v35
	v_add_f32_e32 v38, 1.0, v38
	v_add_f32_e32 v39, 1.0, v39
	v_rcp_f32_e32 v34, v34
	v_rcp_f32_e32 v35, v35
	v_add_f32_e32 v36, 1.0, v36
	v_add_f32_e32 v37, 1.0, v37
	v_cvt_f32_f16_e32 v176, v166
	v_cvt_f32_f16_sdwa v177, v166 dst_sel:DWORD dst_unused:UNUSED_PAD src0_sel:WORD_1
	v_rcp_f32_e32 v38, v38
	v_rcp_f32_e32 v39, v39
	v_rcp_f32_e32 v36, v36
	v_rcp_f32_e32 v37, v37
	v_mul_f32_e32 v30, 0xbfb8aa3b, v30
	v_mul_f32_e32 v31, 0xbfb8aa3b, v31
	s_waitcnt vmcnt(11)
	v_lshlrev_b32_e32 v166, 16, v162
	v_and_b32_e32 v167, 0xffff0000, v162
	v_lshlrev_b32_e32 v162, 16, v163
	v_and_b32_e32 v163, 0xffff0000, v163
	v_mul_f32_e32 v28, 0xbfb8aa3b, v28
	v_mul_f32_e32 v29, 0xbfb8aa3b, v29
	v_exp_f32_e32 v30, v30
	v_exp_f32_e32 v31, v31
	v_mul_f32_e32 v24, 0xbfb8aa3b, v24
	v_mul_f32_e32 v25, 0xbfb8aa3b, v25
	v_pk_fma_f32 v[40:41], v[40:41], v[162:163], v[168:169]
	v_lshlrev_b32_e32 v162, 16, v164
	v_and_b32_e32 v163, 0xffff0000, v164
	v_exp_f32_e32 v28, v28
	v_exp_f32_e32 v29, v29
	v_exp_f32_e32 v24, v24
	v_exp_f32_e32 v25, v25
	v_mul_f32_e32 v26, 0xbfb8aa3b, v26
	v_mul_f32_e32 v27, 0xbfb8aa3b, v27
	v_pk_fma_f32 v[34:35], v[34:35], v[162:163], v[172:173]
	v_lshlrev_b32_e32 v162, 16, v165
	v_and_b32_e32 v163, 0xffff0000, v165
	v_exp_f32_e32 v26, v26
	v_exp_f32_e32 v27, v27
	v_pk_fma_f32 v[38:39], v[38:39], v[166:167], v[176:177]
	v_pk_fma_f32 v[36:37], v[36:37], v[162:163], v[170:171]
	v_cvt_pk_f16_f32 v164, v34, v35
	v_cvt_pk_f16_f32 v165, v36, v37
	v_cvt_pk_f16_f32 v163, v40, v41
	v_cvt_pk_f16_f32 v162, v38, v39
	v_add_f32_e32 v30, 1.0, v30
	v_add_f32_e32 v31, 1.0, v31
	global_store_dwordx4 v[174:175], v[162:165], off offset:256
	v_add_f32_e32 v28, 1.0, v28
	v_add_f32_e32 v29, 1.0, v29
	s_waitcnt vmcnt(11)
	v_cvt_f32_f16_e32 v162, v161
	v_cvt_f32_f16_sdwa v163, v161 dst_sel:DWORD dst_unused:UNUSED_PAD src0_sel:WORD_1
	v_cvt_f32_f16_e32 v164, v160
	v_cvt_f32_f16_sdwa v165, v160 dst_sel:DWORD dst_unused:UNUSED_PAD src0_sel:WORD_1
	v_cvt_f32_f16_e32 v160, v159
	v_cvt_f32_f16_sdwa v161, v159 dst_sel:DWORD dst_unused:UNUSED_PAD src0_sel:WORD_1
	v_rcp_f32_e32 v30, v30
	v_rcp_f32_e32 v31, v31
	v_add_f32_e32 v24, 1.0, v24
	v_add_f32_e32 v25, 1.0, v25
	v_cvt_f32_f16_e32 v166, v158
	v_cvt_f32_f16_sdwa v167, v158 dst_sel:DWORD dst_unused:UNUSED_PAD src0_sel:WORD_1
	v_rcp_f32_e32 v28, v28
	v_rcp_f32_e32 v29, v29
	v_rcp_f32_e32 v24, v24
	v_rcp_f32_e32 v25, v25
	v_add_f32_e32 v26, 1.0, v26
	v_add_f32_e32 v27, 1.0, v27
	v_rcp_f32_e32 v26, v26
	v_rcp_f32_e32 v27, v27
	v_mul_f32_e32 v22, 0xbfb8aa3b, v22
	v_mul_f32_e32 v23, 0xbfb8aa3b, v23
	s_waitcnt vmcnt(10)
	v_lshlrev_b32_e32 v158, 16, v154
	v_and_b32_e32 v159, 0xffff0000, v154
	v_lshlrev_b32_e32 v154, 16, v155
	v_and_b32_e32 v155, 0xffff0000, v155
	v_exp_f32_e32 v22, v22
	v_exp_f32_e32 v23, v23
	v_mul_f32_e32 v16, 0xbfb8aa3b, v16
	v_mul_f32_e32 v17, 0xbfb8aa3b, v17
	v_pk_fma_f32 v[30:31], v[30:31], v[154:155], v[160:161]
	v_lshlrev_b32_e32 v154, 16, v156
	v_and_b32_e32 v155, 0xffff0000, v156
	v_mul_f32_e32 v20, 0xbfb8aa3b, v20
	v_mul_f32_e32 v21, 0xbfb8aa3b, v21
	v_exp_f32_e32 v16, v16
	v_exp_f32_e32 v17, v17
	v_mul_f32_e32 v18, 0xbfb8aa3b, v18
	v_mul_f32_e32 v19, 0xbfb8aa3b, v19
	v_pk_fma_f32 v[28:29], v[28:29], v[158:159], v[166:167]
	v_pk_fma_f32 v[24:25], v[24:25], v[154:155], v[164:165]
	v_lshlrev_b32_e32 v154, 16, v157
	v_and_b32_e32 v155, 0xffff0000, v157
	v_lshlrev_b64 v[158:159], 12, v[202:203]
	v_exp_f32_e32 v20, v20
	v_exp_f32_e32 v21, v21
	v_exp_f32_e32 v18, v18
	v_exp_f32_e32 v19, v19
	v_pk_fma_f32 v[26:27], v[26:27], v[154:155], v[162:163]
	v_lshl_add_u64 v[158:159], s[8:9], 0, v[158:159]
	v_cvt_pk_f16_f32 v157, v26, v27
	v_cvt_pk_f16_f32 v156, v24, v25
	v_cvt_pk_f16_f32 v155, v30, v31
	v_cvt_pk_f16_f32 v154, v28, v29
	v_lshl_add_u64 v[158:159], v[158:159], 0, v[186:187]
	v_add_f32_e32 v22, 1.0, v22
	v_add_f32_e32 v23, 1.0, v23
	global_store_dwordx4 v[158:159], v[154:157], off
	v_rcp_f32_e32 v22, v22
	v_rcp_f32_e32 v23, v23
	s_waitcnt vmcnt(10)
	v_cvt_f32_f16_e32 v154, v153
	v_cvt_f32_f16_sdwa v155, v153 dst_sel:DWORD dst_unused:UNUSED_PAD src0_sel:WORD_1
	v_cvt_f32_f16_e32 v156, v152
	v_cvt_f32_f16_sdwa v157, v152 dst_sel:DWORD dst_unused:UNUSED_PAD src0_sel:WORD_1
	v_cvt_f32_f16_e32 v152, v151
	v_cvt_f32_f16_sdwa v153, v151 dst_sel:DWORD dst_unused:UNUSED_PAD src0_sel:WORD_1
	v_add_f32_e32 v16, 1.0, v16
	v_add_f32_e32 v17, 1.0, v17
	v_add_f32_e32 v20, 1.0, v20
	v_add_f32_e32 v21, 1.0, v21
	v_rcp_f32_e32 v16, v16
	v_rcp_f32_e32 v17, v17
	v_add_f32_e32 v18, 1.0, v18
	v_add_f32_e32 v19, 1.0, v19
	v_cvt_f32_f16_e32 v160, v150
	v_cvt_f32_f16_sdwa v161, v150 dst_sel:DWORD dst_unused:UNUSED_PAD src0_sel:WORD_1
	v_rcp_f32_e32 v20, v20
	v_rcp_f32_e32 v21, v21
	v_rcp_f32_e32 v18, v18
	v_rcp_f32_e32 v19, v19
	v_mul_f32_e32 v14, 0xbfb8aa3b, v14
	v_mul_f32_e32 v15, 0xbfb8aa3b, v15
	s_waitcnt vmcnt(9)
; __device__ __forceinline__ float bf_lo(unsigned w) { return __uint_as_float(w << 16); }
; __device__ __forceinline__ float bf_hi(unsigned w) { return __uint_as_float(w & 0xffff0000u); }
; __device__ __forceinline__ float sigmoidf_fast(float x) { return __builtin_amdgcn_rcpf(1.0f + __expf(-x)); }
;     __device__ __forceinline__ void run(const f32x4 (&v)[2][2][4][2], const Unit& u, int wr, int wc, int fr, int fq, PG8_LAS unsigned char* lds, int wid, int lane, float inv_n, float eps) const {
;     ...
;                 float s = 0.f;
; #pragma unroll
;                 for (int bj = 0; bj < 2; ++bj)
; #pragma unroll
;                     for (int n = 0; n < 2; ++n) { const f32x4 x = v[ai][bj][m][n]; s += (x[0] * x[0] + x[1] * x[1]) + (x[2] * x[2] + x[3] * x[3]); }
;                 s += __shfl_xor(s, 16); s += __shfl_xor(s, 32);
;                 if (fq == 0) P[(ai * HALF + wr * 64 + m * 16 + fr) * 4 + wc] = s;
;     __device__ __forceinline__ void fused(f32x4 (&acc)[2][2][4][2], const Unit& u, int wr, int wc, int fr, int fq, PG8_LAS unsigned char* lds, int wid, int lane) const {
;     ...
;             for (int m = 0; m < 4; ++m) { const size_t off = (size_t)(u.pm * BM + ai * HALF + wr * 64 + m * 16 + fr) * ld + col0;
; #pragma unroll
;                 for (int bj = 0; bj < 2; ++bj) { const f32x8 hv = __builtin_convertvector(hraw[m][bj], f32x8); f32x8 r8;
; #pragma unroll
;                     for (int n = 0; n < 2; ++n) { f32x4 r; const f32x4 a = acc[ai][bj][m][n];
;                         if (MODE == 0) { r[0] = hv[4 * n] + a[0]; r[1] = hv[4 * n + 1] + a[1]; r[2] = hv[4 * n + 2] + a[2]; r[3] = hv[4 * n + 3] + a[3]; }
;                         else { const unsigned e0 = n ? eraw[m][bj].z : eraw[m][bj].x, e1 = n ? eraw[m][bj].w : eraw[m][bj].y;
;                             r[0] = hv[4 * n] + sigmoidf_fast(a[0]) * bf_lo(e0); r[1] = hv[4 * n + 1] + sigmoidf_fast(a[1]) * bf_hi(e0); r[2] = hv[4 * n + 2] + sigmoidf_fast(a[2]) * bf_lo(e1); r[3] = hv[4 * n + 3] + sigmoidf_fast(a[3]) * bf_hi(e1); }
;                         acc[ai][bj][m][n] = r; r8[4 * n] = r[0]; r8[4 * n + 1] = r[1]; r8[4 * n + 2] = r[2]; r8[4 * n + 3] = r[3]; }
;                     *(h16x8*)(H + off + bj * HALF) = __builtin_convertvector(r8, h16x8); }
;                 asm volatile("" : "+v"(acc[ai][0][m][0]), "+v"(acc[ai][0][m][1]), "+v"(acc[ai][1][m][0]), "+v"(acc[ai][1][m][1])); }
	v_lshlrev_b32_e32 v150, 16, v146
	v_and_b32_e32 v151, 0xffff0000, v146
	v_lshlrev_b32_e32 v146, 16, v147
	v_and_b32_e32 v147, 0xffff0000, v147
	v_mul_f32_e32 v12, 0xbfb8aa3b, v12
	v_mul_f32_e32 v13, 0xbfb8aa3b, v13
	v_exp_f32_e32 v14, v14
	v_exp_f32_e32 v15, v15
	v_mul_f32_e32 v8, 0xbfb8aa3b, v8
	v_mul_f32_e32 v9, 0xbfb8aa3b, v9
	v_pk_fma_f32 v[22:23], v[22:23], v[146:147], v[152:153]
	v_lshlrev_b32_e32 v146, 16, v148
	v_and_b32_e32 v147, 0xffff0000, v148
	v_exp_f32_e32 v12, v12
	v_exp_f32_e32 v13, v13
	v_exp_f32_e32 v8, v8
	v_exp_f32_e32 v9, v9
	v_mul_f32_e32 v10, 0xbfb8aa3b, v10
	v_mul_f32_e32 v11, 0xbfb8aa3b, v11
	v_pk_fma_f32 v[16:17], v[16:17], v[146:147], v[156:157]
	v_lshlrev_b32_e32 v146, 16, v149
	v_and_b32_e32 v147, 0xffff0000, v149
	v_exp_f32_e32 v10, v10
	v_exp_f32_e32 v11, v11
	v_pk_fma_f32 v[20:21], v[20:21], v[150:151], v[160:161]
	v_pk_fma_f32 v[18:19], v[18:19], v[146:147], v[154:155]
	v_cvt_pk_f16_f32 v148, v16, v17
	v_cvt_pk_f16_f32 v149, v18, v19
	v_cvt_pk_f16_f32 v147, v22, v23
	v_cvt_pk_f16_f32 v146, v20, v21
	v_add_f32_e32 v14, 1.0, v14
	v_add_f32_e32 v15, 1.0, v15
	global_store_dwordx4 v[158:159], v[146:149], off offset:256
	v_add_f32_e32 v12, 1.0, v12
	v_add_f32_e32 v13, 1.0, v13
	s_waitcnt vmcnt(9)
	v_cvt_f32_f16_e32 v146, v145
	v_cvt_f32_f16_sdwa v147, v145 dst_sel:DWORD dst_unused:UNUSED_PAD src0_sel:WORD_1
	v_cvt_f32_f16_e32 v148, v144
	v_cvt_f32_f16_sdwa v149, v144 dst_sel:DWORD dst_unused:UNUSED_PAD src0_sel:WORD_1
	v_cvt_f32_f16_e32 v144, v143
	v_cvt_f32_f16_sdwa v145, v143 dst_sel:DWORD dst_unused:UNUSED_PAD src0_sel:WORD_1
	v_rcp_f32_e32 v14, v14
	v_rcp_f32_e32 v15, v15
	v_add_f32_e32 v8, 1.0, v8
	v_add_f32_e32 v9, 1.0, v9
	v_cvt_f32_f16_e32 v150, v142
	v_cvt_f32_f16_sdwa v151, v142 dst_sel:DWORD dst_unused:UNUSED_PAD src0_sel:WORD_1
	v_rcp_f32_e32 v12, v12
	v_rcp_f32_e32 v13, v13
	v_rcp_f32_e32 v8, v8
	v_rcp_f32_e32 v9, v9
	v_add_f32_e32 v10, 1.0, v10
	v_add_f32_e32 v11, 1.0, v11
	v_rcp_f32_e32 v10, v10
	v_rcp_f32_e32 v11, v11
	v_mul_f32_e32 v6, 0xbfb8aa3b, v6
	v_mul_f32_e32 v7, 0xbfb8aa3b, v7
	s_waitcnt vmcnt(8)
	v_lshlrev_b32_e32 v142, 16, v138
	v_and_b32_e32 v143, 0xffff0000, v138
	v_lshlrev_b32_e32 v138, 16, v139
	v_and_b32_e32 v139, 0xffff0000, v139
	v_exp_f32_e32 v6, v6
	v_exp_f32_e32 v7, v7
	v_mul_f32_e32 v0, 0xbfb8aa3b, v0
	v_mul_f32_e32 v1, 0xbfb8aa3b, v1
	v_pk_fma_f32 v[14:15], v[14:15], v[138:139], v[144:145]
	v_lshlrev_b32_e32 v138, 16, v140
	v_and_b32_e32 v139, 0xffff0000, v140
	v_mul_f32_e32 v4, 0xbfb8aa3b, v4
	v_mul_f32_e32 v5, 0xbfb8aa3b, v5
	v_exp_f32_e32 v0, v0
	v_exp_f32_e32 v1, v1
	v_mul_f32_e32 v2, 0xbfb8aa3b, v2
	v_mul_f32_e32 v3, 0xbfb8aa3b, v3
	v_pk_fma_f32 v[12:13], v[12:13], v[142:143], v[150:151]
	v_pk_fma_f32 v[8:9], v[8:9], v[138:139], v[148:149]
	v_lshlrev_b32_e32 v138, 16, v141
	v_and_b32_e32 v139, 0xffff0000, v141
	v_lshlrev_b64 v[142:143], 12, v[188:189]
	v_exp_f32_e32 v4, v4
	v_exp_f32_e32 v5, v5
	v_exp_f32_e32 v2, v2
	v_exp_f32_e32 v3, v3
	v_pk_fma_f32 v[10:11], v[10:11], v[138:139], v[146:147]
	v_lshl_add_u64 v[142:143], s[8:9], 0, v[142:143]
	v_cvt_pk_f16_f32 v141, v10, v11
	v_cvt_pk_f16_f32 v140, v8, v9
	v_cvt_pk_f16_f32 v139, v14, v15
	v_cvt_pk_f16_f32 v138, v12, v13
	v_lshl_add_u64 v[142:143], v[142:143], 0, v[186:187]
	v_add_f32_e32 v6, 1.0, v6
	v_add_f32_e32 v7, 1.0, v7
	global_store_dwordx4 v[142:143], v[138:141], off
	v_rcp_f32_e32 v6, v6
	v_rcp_f32_e32 v7, v7
	s_waitcnt vmcnt(8)
	v_cvt_f32_f16_e32 v138, v137
	v_cvt_f32_f16_sdwa v139, v137 dst_sel:DWORD dst_unused:UNUSED_PAD src0_sel:WORD_1
	v_cvt_f32_f16_e32 v140, v136
	v_cvt_f32_f16_sdwa v141, v136 dst_sel:DWORD dst_unused:UNUSED_PAD src0_sel:WORD_1
	v_cvt_f32_f16_e32 v136, v135
	v_cvt_f32_f16_sdwa v137, v135 dst_sel:DWORD dst_unused:UNUSED_PAD src0_sel:WORD_1
	v_add_f32_e32 v0, 1.0, v0
	v_add_f32_e32 v1, 1.0, v1
	v_add_f32_e32 v4, 1.0, v4
	v_add_f32_e32 v5, 1.0, v5
	v_rcp_f32_e32 v0, v0
	v_rcp_f32_e32 v1, v1
	v_add_f32_e32 v2, 1.0, v2
	v_add_f32_e32 v3, 1.0, v3
	v_cvt_f32_f16_e32 v144, v134
	v_cvt_f32_f16_sdwa v145, v134 dst_sel:DWORD dst_unused:UNUSED_PAD src0_sel:WORD_1
	v_rcp_f32_e32 v4, v4
	v_rcp_f32_e32 v5, v5
	v_rcp_f32_e32 v2, v2
	v_rcp_f32_e32 v3, v3
	s_waitcnt vmcnt(7)
	v_lshlrev_b32_e32 v134, 16, v130
	v_and_b32_e32 v135, 0xffff0000, v130
	v_lshlrev_b32_e32 v130, 16, v131
	v_and_b32_e32 v131, 0xffff0000, v131
	v_pk_fma_f32 v[6:7], v[6:7], v[130:131], v[136:137]
	v_lshlrev_b32_e32 v130, 16, v132
	v_and_b32_e32 v131, 0xffff0000, v132
	v_pk_fma_f32 v[0:1], v[0:1], v[130:131], v[140:141]
	v_lshlrev_b32_e32 v130, 16, v133
	v_and_b32_e32 v131, 0xffff0000, v133
	v_pk_fma_f32 v[4:5], v[4:5], v[134:135], v[144:145]
	v_pk_fma_f32 v[2:3], v[2:3], v[130:131], v[138:139]
	v_cvt_pk_f16_f32 v132, v0, v1
	v_cvt_pk_f16_f32 v133, v2, v3
	v_cvt_pk_f16_f32 v131, v6, v7
	v_cvt_pk_f16_f32 v130, v4, v5
	global_store_dwordx4 v[142:143], v[130:133], off offset:256
	v_mul_f32_e32 v134, v65, v65
	v_fmac_f32_e32 v134, v64, v64
	v_and_b32_e32 v131, 64, v236
	v_xor_b32_e32 v130, 16, v236
	v_add_u32_e32 v131, 64, v131
	v_cmp_lt_i32_e32 vcc, v130, v131
	v_xor_b32_e32 v132, 32, v236
	v_mul_f32_e32 v133, v57, v57
	v_cndmask_b32_e32 v130, v236, v130, vcc
	v_cmp_lt_i32_e32 vcc, v132, v131
	v_fmac_f32_e32 v133, v56, v56
	v_lshlrev_b32_e32 v130, 2, v130
	v_cndmask_b32_e32 v131, v236, v132, vcc
	v_mul_f32_e32 v132, v55, v55
	v_fmac_f32_e32 v132, v54, v54
	v_add_f32_e32 v132, v132, v133
	v_mul_f32_e32 v133, v63, v63
	v_fmac_f32_e32 v133, v62, v62
	v_add_f32_e32 v133, v133, v134
	v_add_f32_e32 v132, v132, v133
	v_mul_f32_e32 v133, v71, v71
	v_mul_f32_e32 v134, v73, v73
	v_fmac_f32_e32 v133, v70, v70
	v_fmac_f32_e32 v134, v72, v72
	v_add_f32_e32 v133, v133, v134
	v_add_f32_e32 v132, v133, v132
	v_mul_f32_e32 v133, v79, v79
	v_mul_f32_e32 v134, v81, v81
	v_fmac_f32_e32 v133, v78, v78
	v_fmac_f32_e32 v134, v80, v80
	v_add_f32_e32 v133, v133, v134
	v_add_f32_e32 v132, v133, v132
	ds_bpermute_b32 v133, v130, v132
	v_lshlrev_b32_e32 v131, 2, v131
	v_and_b32_e32 v32, 63, v215
	s_waitcnt lgkmcnt(0)
	v_add_f32_e32 v132, v132, v133
	ds_bpermute_b32 v133, v131, v132
	s_lshl_b32 s2, s2, 2
	v_cmp_gt_u32_e32 vcc, 16, v32
	s_add_i32 s2, s2, 0
	s_and_saveexec_b64 s[4:5], vcc
	v_readlane_b32 s36, v255, 23
	v_readlane_b32 s37, v255, 24
	s_cbranch_execz .LBB0_1296
	s_lshl_b32 s8, s19, 10
	s_add_i32 s8, s2, s8
	v_lshl_add_u32 v134, v216, 4, s8
	s_waitcnt lgkmcnt(0)
	v_add_f32_e32 v132, v132, v133
	ds_write_b32 v134, v132
